# all four EpiResid epilogues (FFN1 down, W_out, cross_wo, FFN2 down): bf16 stores widened to dwordx4 via v_permlane16_swap, vmcnt counts re-derived
# speedup vs baseline: 1.0301x; 1.0043x over previous
;     __device__ __forceinline__ void operator()(Acc& acc, const Unit& u, int wr, int wc, int fr, int fq, LAS unsigned char* lds) const {
;         const int col0 = u.pn * BM + wc * 32 + 4 * fq;
;         if (STp) row_stats_table(lds, STp, u.pm);
;         const LAS f32x2* SL = (const LAS f32x2*)(lds + SL_OFF);
;         f32x4 gg[2][2], bb[2][2];
;         if (STp) {
; #pragma unroll
;             for (int bj = 0; bj < 2; ++bj)
; #pragma unroll
;                 for (int n = 0; n < 2; ++n) { gg[bj][n] = *(const GASP f32x4*)(gam + col0 + bj * HALF + n * 16); bb[bj][n] = *(const GASP f32x4*)(bet + col0 + bj * HALF + n * 16); }
;         }
; #pragma unroll
;         for (int ai = 0; ai < 2; ++ai)
; #pragma unroll
;             for (int m = 0; m < 4; ++m) {
;                 const int rl = ai * HALF + wr * 64 + m * 16 + fr, row = u.pm * BM + rl;
;                 const float* rp = (row < split) ? res0 + (size_t)row * D : res1 + (size_t)(row - split) * D;
;                 float* op = out + (size_t)row * D;
;                 f32x2 st = (f32x2){0.f, 1.f}; if (STp) st = SL[rl];
;                 float s = 0.f, q = 0.f;
; #pragma unroll
;                 for (int bj = 0; bj < 2; ++bj)
; #pragma unroll
;                     for (int n = 0; n < 2; ++n) { const int c = col0 + bj * HALF + n * 16; f32x4 r;
;                         if (resb) { const u32x2 w = *(const GASP u32x2*)(resb + (size_t)row * D + c);
;                             r = (f32x4){__uint_as_float(w.x << 16), __uint_as_float(w.x & 0xffff0000u), __uint_as_float(w.y << 16), __uint_as_float(w.y & 0xffff0000u)}; }
;                         else r = *(const GASP f32x4*)(rp + c);
;                         if (STp) r = (r - st[0]) * st[1] * gg[bj][n] + bb[bj][n];
;                         const f32x4 o = r * ALPHA + acc[ai][bj][m][n] * scale;
;                         if (out) *(GASP f32x4*)(op + c) = o;
;                         if (ob) { u32x2 w; w.x = pk2(o[0], o[1]); w.y = pk2(o[2], o[3]); *(GASP u32x2*)(ob + (size_t)row * D + c) = w; }
;                         s += (o[0] + o[1]) + (o[2] + o[3]); q += (o[0] * o[0] + o[1] * o[1]) + (o[2] * o[2] + o[3] * o[3]); }
;                 if (STn) { s += __shfl_xor(s, 16); s += __shfl_xor(s, 32); q += __shfl_xor(q, 16); q += __shfl_xor(q, 32);
;                     if (fq == 0) *(GASP f32x2*)(STn + (size_t)row * 32 + (u.pn * 4 + wc) * 2) = (f32x2){s, q}; }
.LBB0_271:
	v_mbcnt_lo_u32_b32 v238, -1, 0
	v_mbcnt_hi_u32_b32 v238, -1, v238
	v_bfe_u32 v238, v238, 4, 1
	v_mul_u32_u24_e32 v238, 24, v238
	v_mov_b32_e32 v239, 0
	s_lshl_b32 s28, s49, 8
	v_add_u32_e32 v144, s28, v146
	v_ashrrev_i32_e32 v133, 31, v144
	v_cmp_gt_i32_e32 vcc, s41, v144
	v_lshl_or_b32 v142, s48, 8, v148
	v_ashrrev_i32_e32 v143, 31, v142
	v_cndmask_b32_e32 v145, 0, v133, vcc
	v_lshlrev_b64 v[156:157], 11, v[144:145]
	v_lshl_add_u64 v[156:157], s[42:43], 0, v[156:157]
	v_lshl_add_u64 v[158:159], v[142:143], 1, v[156:157]
	global_load_dwordx2 v[160:161], v[158:159], off
	global_load_dwordx2 v[162:163], v[158:159], off offset:32
	global_load_dwordx2 v[164:165], v[158:159], off offset:256
	global_load_dwordx2 v[166:167], v[158:159], off offset:288
	v_and_b32_e32 v156, 64, v155
	v_xor_b32_e32 v133, 16, v155
	v_add_u32_e32 v157, 64, v156
	v_cmp_lt_i32_e32 vcc, v133, v157
	s_lshl_b32 s24, s48, 3
	s_or_b32 s24, s24, s38
	v_cndmask_b32_e32 v133, v155, v133, vcc
	v_lshlrev_b32_e32 v156, 2, v133
	s_ashr_i32 s25, s24, 31
	s_waitcnt vmcnt(0)
	v_lshlrev_b32_e32 v168, 16, v160
	v_and_b32_e32 v169, 0xffff0000, v160
	v_lshlrev_b32_e32 v160, 16, v161
	v_and_b32_e32 v161, 0xffff0000, v161
	v_lshlrev_b32_e32 v170, 16, v162
	v_and_b32_e32 v171, 0xffff0000, v162
	v_lshlrev_b32_e32 v162, 16, v163
	v_and_b32_e32 v163, 0xffff0000, v163
	v_lshlrev_b32_e32 v172, 16, v164
	v_and_b32_e32 v173, 0xffff0000, v164
	v_lshlrev_b32_e32 v164, 16, v165
	v_and_b32_e32 v165, 0xffff0000, v165
	v_lshlrev_b32_e32 v174, 16, v166
	v_and_b32_e32 v175, 0xffff0000, v166
	v_pk_mul_f32 v[168:169], v[168:169], s[20:21] op_sel_hi:[1,0]
	v_pk_mul_f32 v[160:161], v[160:161], s[20:21] op_sel_hi:[1,0]
	v_pk_mul_f32 v[162:163], v[162:163], s[20:21] op_sel_hi:[1,0]
	v_pk_mul_f32 v[164:165], v[164:165], s[20:21] op_sel_hi:[1,0]
	v_lshlrev_b32_e32 v166, 16, v167
	v_and_b32_e32 v167, 0xffff0000, v167
	v_pk_mul_f32 v[170:171], v[170:171], s[20:21] op_sel_hi:[1,0]
	v_pk_mul_f32 v[172:173], v[172:173], s[20:21] op_sel_hi:[1,0]
	v_pk_mul_f32 v[174:175], v[174:175], s[20:21] op_sel_hi:[1,0]
	v_pk_fma_f32 v[126:127], v[126:127], 0.5, v[160:161] op_sel_hi:[1,0,1]
	v_pk_fma_f32 v[124:125], v[124:125], 0.5, v[168:169] op_sel_hi:[1,0,1]
	v_pk_fma_f32 v[122:123], v[122:123], 0.5, v[162:163] op_sel_hi:[1,0,1]
	v_pk_fma_f32 v[118:119], v[118:119], 0.5, v[164:165] op_sel_hi:[1,0,1]
	v_pk_mul_f32 v[166:167], v[166:167], s[20:21] op_sel_hi:[1,0]
	v_pk_fma_f32 v[120:121], v[120:121], 0.5, v[170:171] op_sel_hi:[1,0,1]
	v_pk_fma_f32 v[116:117], v[116:117], 0.5, v[172:173] op_sel_hi:[1,0,1]
	v_pk_fma_f32 v[162:163], v[112:113], 0.5, v[174:175] op_sel_hi:[1,0,1]
	v_cvt_pk_bf16_f32 v228, v124, v125
	v_cvt_pk_bf16_f32 v229, v126, v127
	v_mul_f32_e32 v172, v122, v122
	v_mul_f32_e32 v173, v118, v118
	v_pk_fma_f32 v[160:161], v[114:115], 0.5, v[166:167] op_sel_hi:[1,0,1]
	v_add_f32_e32 v114, v124, v125
	v_add_f32_e32 v164, v126, v127
	v_mul_f32_e32 v167, v124, v124
	v_mul_f32_e32 v125, v125, v125
	v_mul_f32_e32 v169, v126, v126
	v_mul_f32_e32 v127, v127, v127
	v_cvt_pk_bf16_f32 v230, v120, v121
	v_cvt_pk_bf16_f32 v231, v122, v123
	v_mul_f32_e32 v115, v120, v120
	v_mul_f32_e32 v165, v121, v121
	v_mov_b32_e32 v166, v120
	v_mov_b32_e32 v124, v121
	v_mov_b32_e32 v168, v122
	v_mov_b32_e32 v126, v123
	s_nop 1
	v_permlane16_swap_b32_e32 v228, v230
	v_permlane16_swap_b32_e32 v229, v231
	v_lshl_add_u64 v[236:237], v[158:159], 0, v[238:239]
	global_store_dwordx4 v[236:237], v[228:231], off
	v_pk_fma_f32 v[112:113], v[122:123], v[122:123], v[172:173] op_sel_hi:[1,1,0]
	v_cvt_pk_bf16_f32 v232, v116, v117
	v_mul_f32_e32 v177, v116, v116
	v_mul_f32_e32 v179, v117, v117
	v_mul_f32_e32 v181, v119, v119
	v_mov_b32_e32 v176, v116
	v_mov_b32_e32 v178, v117
	v_pk_add_f32 v[116:117], v[166:167], v[124:125]
	v_pk_add_f32 v[120:121], v[168:169], v[126:127]
	v_pk_add_f32 v[114:115], v[114:115], v[164:165]
	v_mov_b32_e32 v133, v113
	v_mov_b32_e32 v172, v118
	v_mov_b32_e32 v180, v119
	v_pk_add_f32 v[122:123], v[176:177], v[178:179]
	v_pk_add_f32 v[116:117], v[116:117], v[120:121]
	v_pk_add_f32 v[112:113], v[114:115], v[132:133]
	v_pk_add_f32 v[114:115], v[172:173], v[180:181]
	v_mul_f32_e32 v183, v162, v162
	v_mul_f32_e32 v185, v163, v163
	v_mul_f32_e32 v187, v160, v160
	v_mul_f32_e32 v189, v161, v161
	v_pk_add_f32 v[112:113], v[116:117], v[112:113]
	v_pk_add_f32 v[114:115], v[122:123], v[114:115]
	v_mov_b32_e32 v182, v162
	v_mov_b32_e32 v184, v163
	v_mov_b32_e32 v186, v160
	v_mov_b32_e32 v188, v161
	v_pk_add_f32 v[112:113], v[112:113], v[114:115]
	v_pk_add_f32 v[114:115], v[182:183], v[184:185]
	v_pk_add_f32 v[116:117], v[186:187], v[188:189]
	v_cvt_pk_bf16_f32 v233, v118, v119
	v_pk_add_f32 v[114:115], v[114:115], v[116:117]
	v_xor_b32_e32 v116, 32, v155
	v_pk_add_f32 v[112:113], v[112:113], v[114:115]
	ds_bpermute_b32 v114, v156, v112
	ds_bpermute_b32 v115, v156, v113
	v_cmp_lt_i32_e32 vcc, v116, v157
	v_cvt_pk_bf16_f32 v234, v162, v163
	v_cvt_pk_bf16_f32 v235, v160, v161
	v_cndmask_b32_e32 v116, v155, v116, vcc
	v_lshlrev_b32_e32 v116, 2, v116
	s_waitcnt lgkmcnt(0)
	v_pk_add_f32 v[112:113], v[112:113], v[114:115]
	ds_bpermute_b32 v114, v116, v112
	ds_bpermute_b32 v115, v116, v113
	s_nop 1
	v_permlane16_swap_b32_e32 v232, v234
	v_permlane16_swap_b32_e32 v233, v235
	global_store_dwordx4 v[236:237], v[232:235], off offset:256
	s_and_saveexec_b64 s[26:27], s[6:7]
	s_cbranch_execz .LBB0_273
	s_waitcnt lgkmcnt(0)
	v_pk_add_f32 v[112:113], v[112:113], v[114:115]
	v_lshlrev_b64 v[114:115], 7, v[144:145]
	v_lshl_add_u64 v[114:115], s[14:15], 0, v[114:115]
	v_lshl_add_u64 v[114:115], s[24:25], 2, v[114:115]
	global_store_dwordx2 v[114:115], v[112:113], off
; #define GASP __attribute__((address_space(1)))
;     __device__ __forceinline__ void operator()(Acc& acc, const Unit& u, int wr, int wc, int fr, int fq, LAS unsigned char* lds) const {
;     ...
;                 const int rl = ai * HALF + wr * 64 + m * 16 + fr, row = u.pm * BM + rl;
;                 const float* rp = (row < split) ? res0 + (size_t)row * D : res1 + (size_t)(row - split) * D;
;                 float* op = out + (size_t)row * D;
;                 f32x2 st = (f32x2){0.f, 1.f}; if (STp) st = SL[rl];
;                 float s = 0.f, q = 0.f;
; #pragma unroll
;                 for (int bj = 0; bj < 2; ++bj)
; #pragma unroll
;                     for (int n = 0; n < 2; ++n) { const int c = col0 + bj * HALF + n * 16; f32x4 r;
;                         if (resb) { const u32x2 w = *(const GASP u32x2*)(resb + (size_t)row * D + c);
;                             r = (f32x4){__uint_as_float(w.x << 16), __uint_as_float(w.x & 0xffff0000u), __uint_as_float(w.y << 16), __uint_as_float(w.y & 0xffff0000u)}; }
;                         else r = *(const GASP f32x4*)(rp + c);
;                         if (STp) r = (r - st[0]) * st[1] * gg[bj][n] + bb[bj][n];
;                         const f32x4 o = r * ALPHA + acc[ai][bj][m][n] * scale;
;                         if (out) *(GASP f32x4*)(op + c) = o;
;                         if (ob) { u32x2 w; w.x = pk2(o[0], o[1]); w.y = pk2(o[2], o[3]); *(GASP u32x2*)(ob + (size_t)row * D + c) = w; }
;                         s += (o[0] + o[1]) + (o[2] + o[3]); q += (o[0] * o[0] + o[1] * o[1]) + (o[2] * o[2] + o[3] * o[3]); }
;                 if (STn) { s += __shfl_xor(s, 16); s += __shfl_xor(s, 32); q += __shfl_xor(q, 16); q += __shfl_xor(q, 32);
;                     if (fq == 0) *(GASP f32x2*)(STn + (size_t)row * 32 + (u.pn * 4 + wc) * 2) = (f32x2){s, q}; }
.LBB0_273:
	s_or_b64 exec, exec, s[26:27]
	v_add_u32_e32 v112, s28, v149
	v_ashrrev_i32_e32 v113, 31, v112
	v_cmp_gt_i32_e32 vcc, s41, v112
	s_nop 1
	v_cndmask_b32_e32 v113, 0, v113, vcc
	s_waitcnt lgkmcnt(0)
	v_lshlrev_b64 v[114:115], 11, v[112:113]
	v_lshl_add_u64 v[114:115], s[42:43], 0, v[114:115]
	v_lshl_add_u64 v[114:115], v[142:143], 1, v[114:115]
	global_load_dwordx2 v[118:119], v[114:115], off
	global_load_dwordx2 v[120:121], v[114:115], off offset:32
	global_load_dwordx2 v[122:123], v[114:115], off offset:256
	global_load_dwordx2 v[124:125], v[114:115], off offset:288
	s_waitcnt vmcnt(3)
	v_lshlrev_b32_e32 v126, 16, v118
	s_waitcnt vmcnt(2)
	v_lshlrev_b32_e32 v158, 16, v120
	v_and_b32_e32 v159, 0xffff0000, v120
	v_lshlrev_b32_e32 v120, 16, v121
	v_and_b32_e32 v121, 0xffff0000, v121
	v_and_b32_e32 v127, 0xffff0000, v118
	v_lshlrev_b32_e32 v118, 16, v119
	v_and_b32_e32 v119, 0xffff0000, v119
	s_waitcnt vmcnt(1)
	v_lshlrev_b32_e32 v160, 16, v122
	v_and_b32_e32 v161, 0xffff0000, v122
	v_pk_mul_f32 v[120:121], v[120:121], s[20:21] op_sel_hi:[1,0]
	v_lshlrev_b32_e32 v122, 16, v123
	v_and_b32_e32 v123, 0xffff0000, v123
	s_waitcnt vmcnt(0)
	v_lshlrev_b32_e32 v162, 16, v124
	v_and_b32_e32 v163, 0xffff0000, v124
	v_lshlrev_b32_e32 v124, 16, v125
	v_and_b32_e32 v125, 0xffff0000, v125
	v_pk_mul_f32 v[126:127], v[126:127], s[20:21] op_sel_hi:[1,0]
	v_pk_mul_f32 v[118:119], v[118:119], s[20:21] op_sel_hi:[1,0]
	v_pk_mul_f32 v[158:159], v[158:159], s[20:21] op_sel_hi:[1,0]
	v_pk_mul_f32 v[160:161], v[160:161], s[20:21] op_sel_hi:[1,0]
	v_pk_fma_f32 v[106:107], v[106:107], 0.5, v[120:121] op_sel_hi:[1,0,1]
	v_pk_mul_f32 v[122:123], v[122:123], s[20:21] op_sel_hi:[1,0]
	v_pk_mul_f32 v[162:163], v[162:163], s[20:21] op_sel_hi:[1,0]
	v_pk_mul_f32 v[124:125], v[124:125], s[20:21] op_sel_hi:[1,0]
	v_pk_fma_f32 v[110:111], v[110:111], 0.5, v[118:119] op_sel_hi:[1,0,1]
	v_pk_fma_f32 v[108:109], v[108:109], 0.5, v[126:127] op_sel_hi:[1,0,1]
	v_pk_fma_f32 v[104:105], v[104:105], 0.5, v[158:159] op_sel_hi:[1,0,1]
	v_pk_fma_f32 v[100:101], v[100:101], 0.5, v[160:161] op_sel_hi:[1,0,1]
	v_mul_f32_e32 v160, v106, v106
	v_pk_fma_f32 v[102:103], v[102:103], 0.5, v[122:123] op_sel_hi:[1,0,1]
	v_pk_fma_f32 v[118:119], v[98:99], 0.5, v[124:125] op_sel_hi:[1,0,1]
	v_pk_fma_f32 v[120:121], v[96:97], 0.5, v[162:163] op_sel_hi:[1,0,1]
	v_cvt_pk_bf16_f32 v228, v108, v109
	v_cvt_pk_bf16_f32 v229, v110, v111
	v_add_f32_e32 v98, v108, v109
	v_add_f32_e32 v122, v110, v111
	v_mul_f32_e32 v125, v108, v108
	v_mul_f32_e32 v109, v109, v109
	v_mul_f32_e32 v127, v110, v110
	v_mul_f32_e32 v111, v111, v111
	v_cvt_pk_bf16_f32 v230, v104, v105
	v_mul_f32_e32 v99, v104, v104
	v_mul_f32_e32 v123, v105, v105
	v_mov_b32_e32 v124, v104
	v_mov_b32_e32 v108, v105
	v_mov_b32_e32 v126, v106
	v_mov_b32_e32 v110, v107
	v_pk_fma_f32 v[104:105], v[106:107], v[106:107], v[160:161] op_sel_hi:[1,1,0]
	v_cvt_pk_bf16_f32 v231, v106, v107
	v_mul_f32_e32 v163, v100, v100
	v_mul_f32_e32 v165, v101, v101
	v_mul_f32_e32 v167, v102, v102
	v_mul_f32_e32 v169, v103, v103
	v_mov_b32_e32 v162, v100
	v_mov_b32_e32 v164, v101
	v_mov_b32_e32 v166, v102
	v_mov_b32_e32 v168, v103
	v_pk_add_f32 v[106:107], v[124:125], v[108:109]
	v_pk_add_f32 v[108:109], v[126:127], v[110:111]
	v_pk_add_f32 v[98:99], v[98:99], v[122:123]
	v_mov_b32_e32 v133, v105
	v_mul_f32_e32 v171, v120, v120
	v_mul_f32_e32 v173, v121, v121
	v_mul_f32_e32 v175, v118, v118
	v_mul_f32_e32 v177, v119, v119
	v_mov_b32_e32 v170, v120
	v_mov_b32_e32 v172, v121
	v_mov_b32_e32 v174, v118
	v_mov_b32_e32 v176, v119
	v_pk_add_f32 v[110:111], v[162:163], v[164:165]
	v_pk_add_f32 v[122:123], v[166:167], v[168:169]
	v_pk_add_f32 v[106:107], v[106:107], v[108:109]
	v_pk_add_f32 v[98:99], v[98:99], v[132:133]
	v_pk_add_f32 v[124:125], v[170:171], v[172:173]
	v_pk_add_f32 v[126:127], v[174:175], v[176:177]
	v_pk_add_f32 v[104:105], v[110:111], v[122:123]
	v_pk_add_f32 v[98:99], v[106:107], v[98:99]
	v_pk_add_f32 v[108:109], v[124:125], v[126:127]
	v_pk_add_f32 v[98:99], v[98:99], v[104:105]
	s_nop 1
	v_permlane16_swap_b32_e32 v228, v230
	v_permlane16_swap_b32_e32 v229, v231
	v_lshl_add_u64 v[236:237], v[114:115], 0, v[238:239]
	global_store_dwordx4 v[236:237], v[228:231], off
	v_pk_add_f32 v[98:99], v[98:99], v[108:109]
	ds_bpermute_b32 v104, v156, v98
	ds_bpermute_b32 v105, v156, v99
	v_cvt_pk_bf16_f32 v232, v100, v101
	v_cvt_pk_bf16_f32 v233, v102, v103
	v_cvt_pk_bf16_f32 v234, v120, v121
	s_waitcnt lgkmcnt(0)
	v_pk_add_f32 v[96:97], v[98:99], v[104:105]
	ds_bpermute_b32 v98, v116, v96
	ds_bpermute_b32 v99, v116, v97
	v_cvt_pk_bf16_f32 v235, v118, v119
	s_nop 1
	v_permlane16_swap_b32_e32 v232, v234
	v_permlane16_swap_b32_e32 v233, v235
	global_store_dwordx4 v[236:237], v[232:235], off offset:256
	s_and_saveexec_b64 s[26:27], s[6:7]
	s_cbranch_execz .LBB0_275
	s_waitcnt lgkmcnt(0)
	v_pk_add_f32 v[96:97], v[96:97], v[98:99]
	v_lshlrev_b64 v[98:99], 7, v[112:113]
	v_lshl_add_u64 v[98:99], s[14:15], 0, v[98:99]
	v_lshl_add_u64 v[98:99], s[24:25], 2, v[98:99]
	global_store_dwordx2 v[98:99], v[96:97], off
; #define GASP __attribute__((address_space(1)))
;     __device__ __forceinline__ void operator()(Acc& acc, const Unit& u, int wr, int wc, int fr, int fq, LAS unsigned char* lds) const {
;     ...
;                 const int rl = ai * HALF + wr * 64 + m * 16 + fr, row = u.pm * BM + rl;
;                 const float* rp = (row < split) ? res0 + (size_t)row * D : res1 + (size_t)(row - split) * D;
;                 float* op = out + (size_t)row * D;
;                 f32x2 st = (f32x2){0.f, 1.f}; if (STp) st = SL[rl];
;                 float s = 0.f, q = 0.f;
; #pragma unroll
;                 for (int bj = 0; bj < 2; ++bj)
; #pragma unroll
;                     for (int n = 0; n < 2; ++n) { const int c = col0 + bj * HALF + n * 16; f32x4 r;
;                         if (resb) { const u32x2 w = *(const GASP u32x2*)(resb + (size_t)row * D + c);
;                             r = (f32x4){__uint_as_float(w.x << 16), __uint_as_float(w.x & 0xffff0000u), __uint_as_float(w.y << 16), __uint_as_float(w.y & 0xffff0000u)}; }
;                         else r = *(const GASP f32x4*)(rp + c);
;                         if (STp) r = (r - st[0]) * st[1] * gg[bj][n] + bb[bj][n];
;                         const f32x4 o = r * ALPHA + acc[ai][bj][m][n] * scale;
;                         if (out) *(GASP f32x4*)(op + c) = o;
;                         if (ob) { u32x2 w; w.x = pk2(o[0], o[1]); w.y = pk2(o[2], o[3]); *(GASP u32x2*)(ob + (size_t)row * D + c) = w; }
;                         s += (o[0] + o[1]) + (o[2] + o[3]); q += (o[0] * o[0] + o[1] * o[1]) + (o[2] * o[2] + o[3] * o[3]); }
;                 if (STn) { s += __shfl_xor(s, 16); s += __shfl_xor(s, 32); q += __shfl_xor(q, 16); q += __shfl_xor(q, 32);
;                     if (fq == 0) *(GASP f32x2*)(STn + (size_t)row * 32 + (u.pn * 4 + wc) * 2) = (f32x2){s, q}; }
.LBB0_275:
	s_or_b64 exec, exec, s[26:27]
	v_add_u32_e32 v96, s28, v150
	v_ashrrev_i32_e32 v97, 31, v96
	v_cmp_gt_i32_e32 vcc, s41, v96
	s_nop 1
	v_cndmask_b32_e32 v97, 0, v97, vcc
	s_waitcnt lgkmcnt(0)
	v_lshlrev_b64 v[98:99], 11, v[96:97]
	v_lshl_add_u64 v[98:99], s[42:43], 0, v[98:99]
	v_lshl_add_u64 v[98:99], v[142:143], 1, v[98:99]
	global_load_dwordx2 v[100:101], v[98:99], off
	global_load_dwordx2 v[102:103], v[98:99], off offset:32
	global_load_dwordx2 v[104:105], v[98:99], off offset:256
	global_load_dwordx2 v[106:107], v[98:99], off offset:288
	s_waitcnt vmcnt(3)
	v_lshlrev_b32_e32 v108, 16, v100
	s_waitcnt vmcnt(2)
	v_lshlrev_b32_e32 v110, 16, v102
	v_and_b32_e32 v111, 0xffff0000, v102
	v_lshlrev_b32_e32 v102, 16, v103
	v_and_b32_e32 v103, 0xffff0000, v103
	v_and_b32_e32 v109, 0xffff0000, v100
	v_lshlrev_b32_e32 v100, 16, v101
	v_and_b32_e32 v101, 0xffff0000, v101
	s_waitcnt vmcnt(1)
	v_lshlrev_b32_e32 v112, 16, v104
	v_and_b32_e32 v113, 0xffff0000, v104
	v_pk_mul_f32 v[102:103], v[102:103], s[20:21] op_sel_hi:[1,0]
	v_lshlrev_b32_e32 v104, 16, v105
	v_and_b32_e32 v105, 0xffff0000, v105
	s_waitcnt vmcnt(0)
	v_lshlrev_b32_e32 v114, 16, v106
	v_and_b32_e32 v115, 0xffff0000, v106
	v_lshlrev_b32_e32 v106, 16, v107
	v_and_b32_e32 v107, 0xffff0000, v107
	v_pk_mul_f32 v[108:109], v[108:109], s[20:21] op_sel_hi:[1,0]
	v_pk_mul_f32 v[100:101], v[100:101], s[20:21] op_sel_hi:[1,0]
	v_pk_mul_f32 v[110:111], v[110:111], s[20:21] op_sel_hi:[1,0]
	v_pk_mul_f32 v[112:113], v[112:113], s[20:21] op_sel_hi:[1,0]
	v_pk_fma_f32 v[90:91], v[90:91], 0.5, v[102:103] op_sel_hi:[1,0,1]
	v_pk_mul_f32 v[104:105], v[104:105], s[20:21] op_sel_hi:[1,0]
	v_pk_mul_f32 v[114:115], v[114:115], s[20:21] op_sel_hi:[1,0]
	v_pk_mul_f32 v[106:107], v[106:107], s[20:21] op_sel_hi:[1,0]
	v_pk_fma_f32 v[94:95], v[94:95], 0.5, v[100:101] op_sel_hi:[1,0,1]
	v_pk_fma_f32 v[92:93], v[92:93], 0.5, v[108:109] op_sel_hi:[1,0,1]
	v_pk_fma_f32 v[88:89], v[88:89], 0.5, v[110:111] op_sel_hi:[1,0,1]
	v_pk_fma_f32 v[84:85], v[84:85], 0.5, v[112:113] op_sel_hi:[1,0,1]
	v_mul_f32_e32 v112, v90, v90
	v_pk_fma_f32 v[86:87], v[86:87], 0.5, v[104:105] op_sel_hi:[1,0,1]
	v_pk_fma_f32 v[100:101], v[82:83], 0.5, v[106:107] op_sel_hi:[1,0,1]
	v_pk_fma_f32 v[102:103], v[80:81], 0.5, v[114:115] op_sel_hi:[1,0,1]
	v_cvt_pk_bf16_f32 v228, v92, v93
	v_cvt_pk_bf16_f32 v229, v94, v95
	v_add_f32_e32 v82, v92, v93
	v_add_f32_e32 v104, v94, v95
	v_mul_f32_e32 v107, v92, v92
	v_mul_f32_e32 v93, v93, v93
	v_mul_f32_e32 v109, v94, v94
	v_mul_f32_e32 v95, v95, v95
	v_cvt_pk_bf16_f32 v230, v88, v89
	v_mul_f32_e32 v83, v88, v88
	v_mul_f32_e32 v105, v89, v89
	v_mov_b32_e32 v106, v88
	v_mov_b32_e32 v92, v89
	v_mov_b32_e32 v108, v90
	v_mov_b32_e32 v94, v91
	v_pk_fma_f32 v[88:89], v[90:91], v[90:91], v[112:113] op_sel_hi:[1,1,0]
	v_cvt_pk_bf16_f32 v231, v90, v91
	v_mul_f32_e32 v115, v84, v84
	v_mul_f32_e32 v119, v85, v85
	v_mul_f32_e32 v121, v86, v86
	v_mul_f32_e32 v123, v87, v87
	v_mov_b32_e32 v114, v84
	v_mov_b32_e32 v118, v85
	v_mov_b32_e32 v120, v86
	v_mov_b32_e32 v122, v87
	v_pk_add_f32 v[90:91], v[106:107], v[92:93]
	v_pk_add_f32 v[92:93], v[108:109], v[94:95]
	v_pk_add_f32 v[82:83], v[82:83], v[104:105]
	v_mov_b32_e32 v133, v89
	v_mul_f32_e32 v125, v102, v102
	v_mul_f32_e32 v127, v103, v103
	v_mul_f32_e32 v159, v100, v100
	v_mul_f32_e32 v161, v101, v101
	v_mov_b32_e32 v124, v102
	v_mov_b32_e32 v126, v103
	v_mov_b32_e32 v158, v100
	v_mov_b32_e32 v160, v101
	v_pk_add_f32 v[94:95], v[114:115], v[118:119]
	v_pk_add_f32 v[104:105], v[120:121], v[122:123]
	v_pk_add_f32 v[90:91], v[90:91], v[92:93]
	v_pk_add_f32 v[82:83], v[82:83], v[132:133]
	v_pk_add_f32 v[106:107], v[124:125], v[126:127]
	v_pk_add_f32 v[108:109], v[158:159], v[160:161]
	v_pk_add_f32 v[88:89], v[94:95], v[104:105]
	v_pk_add_f32 v[82:83], v[90:91], v[82:83]
	v_pk_add_f32 v[92:93], v[106:107], v[108:109]
	v_pk_add_f32 v[82:83], v[82:83], v[88:89]
	s_nop 1
	v_permlane16_swap_b32_e32 v228, v230
	v_permlane16_swap_b32_e32 v229, v231
	v_lshl_add_u64 v[236:237], v[98:99], 0, v[238:239]
	global_store_dwordx4 v[236:237], v[228:231], off
	v_pk_add_f32 v[82:83], v[82:83], v[92:93]
	ds_bpermute_b32 v88, v156, v82
	ds_bpermute_b32 v89, v156, v83
	v_cvt_pk_bf16_f32 v232, v84, v85
	v_cvt_pk_bf16_f32 v233, v86, v87
	v_cvt_pk_bf16_f32 v234, v102, v103
	s_waitcnt lgkmcnt(0)
	v_pk_add_f32 v[80:81], v[82:83], v[88:89]
	ds_bpermute_b32 v82, v116, v80
	ds_bpermute_b32 v83, v116, v81
	v_cvt_pk_bf16_f32 v235, v100, v101
	s_nop 1
	v_permlane16_swap_b32_e32 v232, v234
	v_permlane16_swap_b32_e32 v233, v235
	global_store_dwordx4 v[236:237], v[232:235], off offset:256
	s_and_saveexec_b64 s[26:27], s[6:7]
	s_cbranch_execz .LBB0_277
	s_waitcnt lgkmcnt(0)
	v_pk_add_f32 v[80:81], v[80:81], v[82:83]
	v_lshlrev_b64 v[82:83], 7, v[96:97]
	v_lshl_add_u64 v[82:83], s[14:15], 0, v[82:83]
	v_lshl_add_u64 v[82:83], s[24:25], 2, v[82:83]
	global_store_dwordx2 v[82:83], v[80:81], off
; #define GASP __attribute__((address_space(1)))
;     __device__ __forceinline__ void operator()(Acc& acc, const Unit& u, int wr, int wc, int fr, int fq, LAS unsigned char* lds) const {
;     ...
;                 const int rl = ai * HALF + wr * 64 + m * 16 + fr, row = u.pm * BM + rl;
;                 const float* rp = (row < split) ? res0 + (size_t)row * D : res1 + (size_t)(row - split) * D;
;                 float* op = out + (size_t)row * D;
;                 f32x2 st = (f32x2){0.f, 1.f}; if (STp) st = SL[rl];
;                 float s = 0.f, q = 0.f;
; #pragma unroll
;                 for (int bj = 0; bj < 2; ++bj)
; #pragma unroll
;                     for (int n = 0; n < 2; ++n) { const int c = col0 + bj * HALF + n * 16; f32x4 r;
;                         if (resb) { const u32x2 w = *(const GASP u32x2*)(resb + (size_t)row * D + c);
;                             r = (f32x4){__uint_as_float(w.x << 16), __uint_as_float(w.x & 0xffff0000u), __uint_as_float(w.y << 16), __uint_as_float(w.y & 0xffff0000u)}; }
;                         else r = *(const GASP f32x4*)(rp + c);
;                         if (STp) r = (r - st[0]) * st[1] * gg[bj][n] + bb[bj][n];
;                         const f32x4 o = r * ALPHA + acc[ai][bj][m][n] * scale;
;                         if (out) *(GASP f32x4*)(op + c) = o;
;                         if (ob) { u32x2 w; w.x = pk2(o[0], o[1]); w.y = pk2(o[2], o[3]); *(GASP u32x2*)(ob + (size_t)row * D + c) = w; }
;                         s += (o[0] + o[1]) + (o[2] + o[3]); q += (o[0] * o[0] + o[1] * o[1]) + (o[2] * o[2] + o[3] * o[3]); }
;                 if (STn) { s += __shfl_xor(s, 16); s += __shfl_xor(s, 32); q += __shfl_xor(q, 16); q += __shfl_xor(q, 32);
;                     if (fq == 0) *(GASP f32x2*)(STn + (size_t)row * 32 + (u.pn * 4 + wc) * 2) = (f32x2){s, q}; }
.LBB0_277:
	s_or_b64 exec, exec, s[26:27]
	v_add_u32_e32 v80, s28, v151
	v_ashrrev_i32_e32 v81, 31, v80
	v_cmp_gt_i32_e32 vcc, s41, v80
	s_nop 1
	v_cndmask_b32_e32 v81, 0, v81, vcc
	s_waitcnt lgkmcnt(0)
	v_lshlrev_b64 v[82:83], 11, v[80:81]
	v_lshl_add_u64 v[82:83], s[42:43], 0, v[82:83]
	v_lshl_add_u64 v[82:83], v[142:143], 1, v[82:83]
	global_load_dwordx2 v[84:85], v[82:83], off
	global_load_dwordx2 v[86:87], v[82:83], off offset:32
	global_load_dwordx2 v[88:89], v[82:83], off offset:256
	global_load_dwordx2 v[90:91], v[82:83], off offset:288
	s_waitcnt vmcnt(3)
	v_lshlrev_b32_e32 v92, 16, v84
	s_waitcnt vmcnt(2)
	v_lshlrev_b32_e32 v94, 16, v86
	v_and_b32_e32 v95, 0xffff0000, v86
	v_lshlrev_b32_e32 v86, 16, v87
	v_and_b32_e32 v87, 0xffff0000, v87
	v_and_b32_e32 v93, 0xffff0000, v84
	v_lshlrev_b32_e32 v84, 16, v85
	v_and_b32_e32 v85, 0xffff0000, v85
	s_waitcnt vmcnt(1)
	v_lshlrev_b32_e32 v96, 16, v88
	v_and_b32_e32 v97, 0xffff0000, v88
	v_pk_mul_f32 v[86:87], v[86:87], s[20:21] op_sel_hi:[1,0]
	v_lshlrev_b32_e32 v88, 16, v89
	v_and_b32_e32 v89, 0xffff0000, v89
	s_waitcnt vmcnt(0)
	v_lshlrev_b32_e32 v98, 16, v90
	v_and_b32_e32 v99, 0xffff0000, v90
	v_lshlrev_b32_e32 v90, 16, v91
	v_and_b32_e32 v91, 0xffff0000, v91
	v_pk_mul_f32 v[92:93], v[92:93], s[20:21] op_sel_hi:[1,0]
	v_pk_mul_f32 v[84:85], v[84:85], s[20:21] op_sel_hi:[1,0]
	v_pk_mul_f32 v[94:95], v[94:95], s[20:21] op_sel_hi:[1,0]
	v_pk_mul_f32 v[96:97], v[96:97], s[20:21] op_sel_hi:[1,0]
	v_pk_fma_f32 v[74:75], v[74:75], 0.5, v[86:87] op_sel_hi:[1,0,1]
	v_pk_mul_f32 v[88:89], v[88:89], s[20:21] op_sel_hi:[1,0]
	v_pk_mul_f32 v[98:99], v[98:99], s[20:21] op_sel_hi:[1,0]
	v_pk_mul_f32 v[90:91], v[90:91], s[20:21] op_sel_hi:[1,0]
	v_pk_fma_f32 v[78:79], v[78:79], 0.5, v[84:85] op_sel_hi:[1,0,1]
	v_pk_fma_f32 v[76:77], v[76:77], 0.5, v[92:93] op_sel_hi:[1,0,1]
	v_pk_fma_f32 v[72:73], v[72:73], 0.5, v[94:95] op_sel_hi:[1,0,1]
	v_pk_fma_f32 v[68:69], v[68:69], 0.5, v[96:97] op_sel_hi:[1,0,1]
	v_mul_f32_e32 v96, v74, v74
	v_pk_fma_f32 v[70:71], v[70:71], 0.5, v[88:89] op_sel_hi:[1,0,1]
	v_pk_fma_f32 v[84:85], v[66:67], 0.5, v[90:91] op_sel_hi:[1,0,1]
	v_pk_fma_f32 v[86:87], v[64:65], 0.5, v[98:99] op_sel_hi:[1,0,1]
	v_cvt_pk_bf16_f32 v228, v76, v77
	v_cvt_pk_bf16_f32 v229, v78, v79
	v_add_f32_e32 v66, v76, v77
	v_add_f32_e32 v88, v78, v79
	v_mul_f32_e32 v91, v76, v76
	v_mul_f32_e32 v77, v77, v77
	v_mul_f32_e32 v93, v78, v78
	v_mul_f32_e32 v79, v79, v79
	v_cvt_pk_bf16_f32 v230, v72, v73
	v_mul_f32_e32 v67, v72, v72
	v_mul_f32_e32 v89, v73, v73
	v_mov_b32_e32 v90, v72
	v_mov_b32_e32 v76, v73
	v_mov_b32_e32 v92, v74
	v_mov_b32_e32 v78, v75
	v_pk_fma_f32 v[72:73], v[74:75], v[74:75], v[96:97] op_sel_hi:[1,1,0]
	v_cvt_pk_bf16_f32 v231, v74, v75
	v_mul_f32_e32 v99, v68, v68
	v_mul_f32_e32 v101, v69, v69
	v_mul_f32_e32 v103, v70, v70
	v_mul_f32_e32 v105, v71, v71
	v_mov_b32_e32 v98, v68
	v_mov_b32_e32 v100, v69
	v_mov_b32_e32 v102, v70
	v_mov_b32_e32 v104, v71
	v_pk_add_f32 v[74:75], v[90:91], v[76:77]
	v_pk_add_f32 v[76:77], v[92:93], v[78:79]
	v_pk_add_f32 v[66:67], v[66:67], v[88:89]
	v_mov_b32_e32 v133, v73
	v_mul_f32_e32 v107, v86, v86
	v_mul_f32_e32 v109, v87, v87
	v_mul_f32_e32 v111, v84, v84
	v_mul_f32_e32 v113, v85, v85
	v_mov_b32_e32 v106, v86
	v_mov_b32_e32 v108, v87
	v_mov_b32_e32 v110, v84
	v_mov_b32_e32 v112, v85
	v_pk_add_f32 v[78:79], v[98:99], v[100:101]
	v_pk_add_f32 v[88:89], v[102:103], v[104:105]
	v_pk_add_f32 v[74:75], v[74:75], v[76:77]
	v_pk_add_f32 v[66:67], v[66:67], v[132:133]
	v_pk_add_f32 v[90:91], v[106:107], v[108:109]
	v_pk_add_f32 v[92:93], v[110:111], v[112:113]
	v_pk_add_f32 v[72:73], v[78:79], v[88:89]
	v_pk_add_f32 v[66:67], v[74:75], v[66:67]
	v_pk_add_f32 v[76:77], v[90:91], v[92:93]
	v_pk_add_f32 v[66:67], v[66:67], v[72:73]
	s_nop 1
	v_permlane16_swap_b32_e32 v228, v230
	v_permlane16_swap_b32_e32 v229, v231
	v_lshl_add_u64 v[236:237], v[82:83], 0, v[238:239]
	global_store_dwordx4 v[236:237], v[228:231], off
	v_pk_add_f32 v[66:67], v[66:67], v[76:77]
	ds_bpermute_b32 v72, v156, v66
	ds_bpermute_b32 v73, v156, v67
	v_cvt_pk_bf16_f32 v232, v68, v69
	v_cvt_pk_bf16_f32 v233, v70, v71
	v_cvt_pk_bf16_f32 v234, v86, v87
	s_waitcnt lgkmcnt(0)
	v_pk_add_f32 v[64:65], v[66:67], v[72:73]
	ds_bpermute_b32 v66, v116, v64
	ds_bpermute_b32 v67, v116, v65
	v_cvt_pk_bf16_f32 v235, v84, v85
	s_nop 1
	v_permlane16_swap_b32_e32 v232, v234
	v_permlane16_swap_b32_e32 v233, v235
	global_store_dwordx4 v[236:237], v[232:235], off offset:256
	s_and_saveexec_b64 s[26:27], s[6:7]
	s_cbranch_execz .LBB0_279
	s_waitcnt lgkmcnt(0)
	v_pk_add_f32 v[64:65], v[64:65], v[66:67]
	v_lshlrev_b64 v[66:67], 7, v[80:81]
	v_lshl_add_u64 v[66:67], s[14:15], 0, v[66:67]
	v_lshl_add_u64 v[66:67], s[24:25], 2, v[66:67]
	global_store_dwordx2 v[66:67], v[64:65], off
; #define GASP __attribute__((address_space(1)))
;     __device__ __forceinline__ void operator()(Acc& acc, const Unit& u, int wr, int wc, int fr, int fq, LAS unsigned char* lds) const {
;     ...
;                 const int rl = ai * HALF + wr * 64 + m * 16 + fr, row = u.pm * BM + rl;
;                 const float* rp = (row < split) ? res0 + (size_t)row * D : res1 + (size_t)(row - split) * D;
;                 float* op = out + (size_t)row * D;
;                 f32x2 st = (f32x2){0.f, 1.f}; if (STp) st = SL[rl];
;                 float s = 0.f, q = 0.f;
; #pragma unroll
;                 for (int bj = 0; bj < 2; ++bj)
; #pragma unroll
;                     for (int n = 0; n < 2; ++n) { const int c = col0 + bj * HALF + n * 16; f32x4 r;
;                         if (resb) { const u32x2 w = *(const GASP u32x2*)(resb + (size_t)row * D + c);
;                             r = (f32x4){__uint_as_float(w.x << 16), __uint_as_float(w.x & 0xffff0000u), __uint_as_float(w.y << 16), __uint_as_float(w.y & 0xffff0000u)}; }
;                         else r = *(const GASP f32x4*)(rp + c);
;                         if (STp) r = (r - st[0]) * st[1] * gg[bj][n] + bb[bj][n];
;                         const f32x4 o = r * ALPHA + acc[ai][bj][m][n] * scale;
;                         if (out) *(GASP f32x4*)(op + c) = o;
;                         if (ob) { u32x2 w; w.x = pk2(o[0], o[1]); w.y = pk2(o[2], o[3]); *(GASP u32x2*)(ob + (size_t)row * D + c) = w; }
;                         s += (o[0] + o[1]) + (o[2] + o[3]); q += (o[0] * o[0] + o[1] * o[1]) + (o[2] * o[2] + o[3] * o[3]); }
;                 if (STn) { s += __shfl_xor(s, 16); s += __shfl_xor(s, 32); q += __shfl_xor(q, 16); q += __shfl_xor(q, 32);
;                     if (fq == 0) *(GASP f32x2*)(STn + (size_t)row * 32 + (u.pn * 4 + wc) * 2) = (f32x2){s, q}; }
.LBB0_279:
	s_or_b64 exec, exec, s[26:27]
	v_add_u32_e32 v64, 0x80, v144
	v_ashrrev_i32_e32 v65, 31, v64
	v_cmp_gt_i32_e32 vcc, s41, v64
	s_nop 1
	v_cndmask_b32_e32 v65, 0, v65, vcc
	s_waitcnt lgkmcnt(0)
	v_lshlrev_b64 v[66:67], 11, v[64:65]
	v_lshl_add_u64 v[66:67], s[42:43], 0, v[66:67]
	v_lshl_add_u64 v[66:67], v[142:143], 1, v[66:67]
	global_load_dwordx2 v[68:69], v[66:67], off
	global_load_dwordx2 v[70:71], v[66:67], off offset:32
	global_load_dwordx2 v[72:73], v[66:67], off offset:256
	global_load_dwordx2 v[74:75], v[66:67], off offset:288
	s_waitcnt vmcnt(3)
	v_lshlrev_b32_e32 v76, 16, v68
	s_waitcnt vmcnt(2)
	v_lshlrev_b32_e32 v78, 16, v70
	v_and_b32_e32 v79, 0xffff0000, v70
	v_lshlrev_b32_e32 v70, 16, v71
	v_and_b32_e32 v71, 0xffff0000, v71
	v_and_b32_e32 v77, 0xffff0000, v68
	v_lshlrev_b32_e32 v68, 16, v69
	v_and_b32_e32 v69, 0xffff0000, v69
	s_waitcnt vmcnt(1)
	v_lshlrev_b32_e32 v80, 16, v72
	v_and_b32_e32 v81, 0xffff0000, v72
	v_pk_mul_f32 v[70:71], v[70:71], s[20:21] op_sel_hi:[1,0]
	v_lshlrev_b32_e32 v72, 16, v73
	v_and_b32_e32 v73, 0xffff0000, v73
	s_waitcnt vmcnt(0)
	v_lshlrev_b32_e32 v82, 16, v74
	v_and_b32_e32 v83, 0xffff0000, v74
	v_lshlrev_b32_e32 v74, 16, v75
	v_and_b32_e32 v75, 0xffff0000, v75
	v_pk_mul_f32 v[76:77], v[76:77], s[20:21] op_sel_hi:[1,0]
	v_pk_mul_f32 v[68:69], v[68:69], s[20:21] op_sel_hi:[1,0]
	v_pk_mul_f32 v[78:79], v[78:79], s[20:21] op_sel_hi:[1,0]
	v_pk_mul_f32 v[80:81], v[80:81], s[20:21] op_sel_hi:[1,0]
	v_pk_fma_f32 v[58:59], v[58:59], 0.5, v[70:71] op_sel_hi:[1,0,1]
	v_pk_mul_f32 v[72:73], v[72:73], s[20:21] op_sel_hi:[1,0]
	v_pk_mul_f32 v[82:83], v[82:83], s[20:21] op_sel_hi:[1,0]
	v_pk_mul_f32 v[74:75], v[74:75], s[20:21] op_sel_hi:[1,0]
	v_pk_fma_f32 v[62:63], v[62:63], 0.5, v[68:69] op_sel_hi:[1,0,1]
	v_pk_fma_f32 v[60:61], v[60:61], 0.5, v[76:77] op_sel_hi:[1,0,1]
	v_pk_fma_f32 v[56:57], v[56:57], 0.5, v[78:79] op_sel_hi:[1,0,1]
	v_pk_fma_f32 v[52:53], v[52:53], 0.5, v[80:81] op_sel_hi:[1,0,1]
	v_mul_f32_e32 v80, v58, v58
	v_pk_fma_f32 v[54:55], v[54:55], 0.5, v[72:73] op_sel_hi:[1,0,1]
	v_pk_fma_f32 v[68:69], v[50:51], 0.5, v[74:75] op_sel_hi:[1,0,1]
	v_pk_fma_f32 v[70:71], v[48:49], 0.5, v[82:83] op_sel_hi:[1,0,1]
	v_cvt_pk_bf16_f32 v228, v60, v61
	v_cvt_pk_bf16_f32 v229, v62, v63
	v_add_f32_e32 v50, v60, v61
	v_add_f32_e32 v72, v62, v63
	v_mul_f32_e32 v75, v60, v60
	v_mul_f32_e32 v61, v61, v61
	v_mul_f32_e32 v77, v62, v62
	v_mul_f32_e32 v63, v63, v63
	v_cvt_pk_bf16_f32 v230, v56, v57
	v_mul_f32_e32 v51, v56, v56
	v_mul_f32_e32 v73, v57, v57
	v_mov_b32_e32 v74, v56
	v_mov_b32_e32 v60, v57
	v_mov_b32_e32 v76, v58
	v_mov_b32_e32 v62, v59
	v_pk_fma_f32 v[56:57], v[58:59], v[58:59], v[80:81] op_sel_hi:[1,1,0]
	v_cvt_pk_bf16_f32 v231, v58, v59
	v_mul_f32_e32 v83, v52, v52
	v_mul_f32_e32 v85, v53, v53
	v_mul_f32_e32 v87, v54, v54
	v_mul_f32_e32 v89, v55, v55
	v_mov_b32_e32 v82, v52
	v_mov_b32_e32 v84, v53
	v_mov_b32_e32 v86, v54
	v_mov_b32_e32 v88, v55
	v_pk_add_f32 v[58:59], v[74:75], v[60:61]
	v_pk_add_f32 v[60:61], v[76:77], v[62:63]
	v_pk_add_f32 v[50:51], v[50:51], v[72:73]
	v_mov_b32_e32 v133, v57
	v_mul_f32_e32 v91, v70, v70
	v_mul_f32_e32 v93, v71, v71
	v_mul_f32_e32 v95, v68, v68
	v_mul_f32_e32 v97, v69, v69
	v_mov_b32_e32 v90, v70
	v_mov_b32_e32 v92, v71
	v_mov_b32_e32 v94, v68
	v_mov_b32_e32 v96, v69
	v_pk_add_f32 v[62:63], v[82:83], v[84:85]
	v_pk_add_f32 v[72:73], v[86:87], v[88:89]
	v_pk_add_f32 v[58:59], v[58:59], v[60:61]
	v_pk_add_f32 v[50:51], v[50:51], v[132:133]
	v_pk_add_f32 v[74:75], v[90:91], v[92:93]
	v_pk_add_f32 v[76:77], v[94:95], v[96:97]
	v_pk_add_f32 v[56:57], v[62:63], v[72:73]
	v_pk_add_f32 v[50:51], v[58:59], v[50:51]
	v_pk_add_f32 v[60:61], v[74:75], v[76:77]
	v_pk_add_f32 v[50:51], v[50:51], v[56:57]
	s_nop 1
	v_permlane16_swap_b32_e32 v228, v230
	v_permlane16_swap_b32_e32 v229, v231
	v_lshl_add_u64 v[236:237], v[66:67], 0, v[238:239]
	global_store_dwordx4 v[236:237], v[228:231], off
	v_pk_add_f32 v[50:51], v[50:51], v[60:61]
	ds_bpermute_b32 v56, v156, v50
	ds_bpermute_b32 v57, v156, v51
	v_cvt_pk_bf16_f32 v232, v52, v53
	v_cvt_pk_bf16_f32 v233, v54, v55
	v_cvt_pk_bf16_f32 v234, v70, v71
	s_waitcnt lgkmcnt(0)
	v_pk_add_f32 v[48:49], v[50:51], v[56:57]
	ds_bpermute_b32 v50, v116, v48
	ds_bpermute_b32 v51, v116, v49
	v_cvt_pk_bf16_f32 v235, v68, v69
	s_nop 1
	v_permlane16_swap_b32_e32 v232, v234
	v_permlane16_swap_b32_e32 v233, v235
	global_store_dwordx4 v[236:237], v[232:235], off offset:256
	s_and_saveexec_b64 s[26:27], s[6:7]
	s_cbranch_execz .LBB0_281
	s_waitcnt lgkmcnt(0)
	v_pk_add_f32 v[48:49], v[48:49], v[50:51]
	v_lshlrev_b64 v[50:51], 7, v[64:65]
	v_lshl_add_u64 v[50:51], s[14:15], 0, v[50:51]
	v_lshl_add_u64 v[50:51], s[24:25], 2, v[50:51]
	global_store_dwordx2 v[50:51], v[48:49], off
; #define GASP __attribute__((address_space(1)))
;     __device__ __forceinline__ void operator()(Acc& acc, const Unit& u, int wr, int wc, int fr, int fq, LAS unsigned char* lds) const {
;     ...
;                 const int rl = ai * HALF + wr * 64 + m * 16 + fr, row = u.pm * BM + rl;
;                 const float* rp = (row < split) ? res0 + (size_t)row * D : res1 + (size_t)(row - split) * D;
;                 float* op = out + (size_t)row * D;
;                 f32x2 st = (f32x2){0.f, 1.f}; if (STp) st = SL[rl];
;                 float s = 0.f, q = 0.f;
; #pragma unroll
;                 for (int bj = 0; bj < 2; ++bj)
; #pragma unroll
;                     for (int n = 0; n < 2; ++n) { const int c = col0 + bj * HALF + n * 16; f32x4 r;
;                         if (resb) { const u32x2 w = *(const GASP u32x2*)(resb + (size_t)row * D + c);
;                             r = (f32x4){__uint_as_float(w.x << 16), __uint_as_float(w.x & 0xffff0000u), __uint_as_float(w.y << 16), __uint_as_float(w.y & 0xffff0000u)}; }
;                         else r = *(const GASP f32x4*)(rp + c);
;                         if (STp) r = (r - st[0]) * st[1] * gg[bj][n] + bb[bj][n];
;                         const f32x4 o = r * ALPHA + acc[ai][bj][m][n] * scale;
;                         if (out) *(GASP f32x4*)(op + c) = o;
;                         if (ob) { u32x2 w; w.x = pk2(o[0], o[1]); w.y = pk2(o[2], o[3]); *(GASP u32x2*)(ob + (size_t)row * D + c) = w; }
;                         s += (o[0] + o[1]) + (o[2] + o[3]); q += (o[0] * o[0] + o[1] * o[1]) + (o[2] * o[2] + o[3] * o[3]); }
;                 if (STn) { s += __shfl_xor(s, 16); s += __shfl_xor(s, 32); q += __shfl_xor(q, 16); q += __shfl_xor(q, 32);
;                     if (fq == 0) *(GASP f32x2*)(STn + (size_t)row * 32 + (u.pn * 4 + wc) * 2) = (f32x2){s, q}; }
.LBB0_281:
	s_or_b64 exec, exec, s[26:27]
	v_add_u32_e32 v48, 0x90, v144
	v_ashrrev_i32_e32 v49, 31, v48
	v_cmp_gt_i32_e32 vcc, s41, v48
	s_nop 1
	v_cndmask_b32_e32 v49, 0, v49, vcc
	s_waitcnt lgkmcnt(0)
	v_lshlrev_b64 v[50:51], 11, v[48:49]
	v_lshl_add_u64 v[50:51], s[42:43], 0, v[50:51]
	v_lshl_add_u64 v[50:51], v[142:143], 1, v[50:51]
	global_load_dwordx2 v[52:53], v[50:51], off
	global_load_dwordx2 v[54:55], v[50:51], off offset:32
	global_load_dwordx2 v[56:57], v[50:51], off offset:256
	global_load_dwordx2 v[58:59], v[50:51], off offset:288
	s_waitcnt vmcnt(3)
	v_lshlrev_b32_e32 v60, 16, v52
	s_waitcnt vmcnt(2)
	v_lshlrev_b32_e32 v62, 16, v54
	v_and_b32_e32 v63, 0xffff0000, v54
	v_lshlrev_b32_e32 v54, 16, v55
	v_and_b32_e32 v55, 0xffff0000, v55
	v_and_b32_e32 v61, 0xffff0000, v52
	v_lshlrev_b32_e32 v52, 16, v53
	v_and_b32_e32 v53, 0xffff0000, v53
	s_waitcnt vmcnt(1)
	v_lshlrev_b32_e32 v64, 16, v56
	v_and_b32_e32 v65, 0xffff0000, v56
	v_pk_mul_f32 v[54:55], v[54:55], s[20:21] op_sel_hi:[1,0]
	v_lshlrev_b32_e32 v56, 16, v57
	v_and_b32_e32 v57, 0xffff0000, v57
	s_waitcnt vmcnt(0)
	v_lshlrev_b32_e32 v66, 16, v58
	v_and_b32_e32 v67, 0xffff0000, v58
	v_lshlrev_b32_e32 v58, 16, v59
	v_and_b32_e32 v59, 0xffff0000, v59
	v_pk_mul_f32 v[60:61], v[60:61], s[20:21] op_sel_hi:[1,0]
	v_pk_mul_f32 v[52:53], v[52:53], s[20:21] op_sel_hi:[1,0]
	v_pk_mul_f32 v[62:63], v[62:63], s[20:21] op_sel_hi:[1,0]
	v_pk_mul_f32 v[64:65], v[64:65], s[20:21] op_sel_hi:[1,0]
	v_pk_fma_f32 v[42:43], v[42:43], 0.5, v[54:55] op_sel_hi:[1,0,1]
	v_pk_mul_f32 v[56:57], v[56:57], s[20:21] op_sel_hi:[1,0]
	v_pk_mul_f32 v[66:67], v[66:67], s[20:21] op_sel_hi:[1,0]
	v_pk_mul_f32 v[58:59], v[58:59], s[20:21] op_sel_hi:[1,0]
	v_pk_fma_f32 v[46:47], v[46:47], 0.5, v[52:53] op_sel_hi:[1,0,1]
	v_pk_fma_f32 v[44:45], v[44:45], 0.5, v[60:61] op_sel_hi:[1,0,1]
	v_pk_fma_f32 v[40:41], v[40:41], 0.5, v[62:63] op_sel_hi:[1,0,1]
	v_pk_fma_f32 v[36:37], v[36:37], 0.5, v[64:65] op_sel_hi:[1,0,1]
	v_mul_f32_e32 v64, v42, v42
	v_pk_fma_f32 v[38:39], v[38:39], 0.5, v[56:57] op_sel_hi:[1,0,1]
	v_pk_fma_f32 v[52:53], v[34:35], 0.5, v[58:59] op_sel_hi:[1,0,1]
	v_pk_fma_f32 v[54:55], v[32:33], 0.5, v[66:67] op_sel_hi:[1,0,1]
	v_cvt_pk_bf16_f32 v228, v44, v45
	v_cvt_pk_bf16_f32 v229, v46, v47
	v_add_f32_e32 v34, v44, v45
	v_add_f32_e32 v56, v46, v47
	v_mul_f32_e32 v59, v44, v44
	v_mul_f32_e32 v45, v45, v45
	v_mul_f32_e32 v61, v46, v46
	v_mul_f32_e32 v47, v47, v47
	v_cvt_pk_bf16_f32 v230, v40, v41
	v_mul_f32_e32 v35, v40, v40
	v_mul_f32_e32 v57, v41, v41
	v_mov_b32_e32 v58, v40
	v_mov_b32_e32 v44, v41
	v_mov_b32_e32 v60, v42
	v_mov_b32_e32 v46, v43
	v_pk_fma_f32 v[40:41], v[42:43], v[42:43], v[64:65] op_sel_hi:[1,1,0]
	v_cvt_pk_bf16_f32 v231, v42, v43
	v_mul_f32_e32 v67, v36, v36
	v_mul_f32_e32 v69, v37, v37
	v_mul_f32_e32 v71, v38, v38
	v_mul_f32_e32 v73, v39, v39
	v_mov_b32_e32 v66, v36
	v_mov_b32_e32 v68, v37
	v_mov_b32_e32 v70, v38
	v_mov_b32_e32 v72, v39
	v_pk_add_f32 v[42:43], v[58:59], v[44:45]
	v_pk_add_f32 v[44:45], v[60:61], v[46:47]
	v_pk_add_f32 v[34:35], v[34:35], v[56:57]
	v_mov_b32_e32 v133, v41
	v_mul_f32_e32 v75, v54, v54
	v_mul_f32_e32 v77, v55, v55
	v_mul_f32_e32 v79, v52, v52
	v_mul_f32_e32 v81, v53, v53
	v_mov_b32_e32 v74, v54
	v_mov_b32_e32 v76, v55
	v_mov_b32_e32 v78, v52
	v_mov_b32_e32 v80, v53
	v_pk_add_f32 v[46:47], v[66:67], v[68:69]
	v_pk_add_f32 v[56:57], v[70:71], v[72:73]
	v_pk_add_f32 v[42:43], v[42:43], v[44:45]
	v_pk_add_f32 v[34:35], v[34:35], v[132:133]
	v_pk_add_f32 v[58:59], v[74:75], v[76:77]
	v_pk_add_f32 v[60:61], v[78:79], v[80:81]
	v_pk_add_f32 v[40:41], v[46:47], v[56:57]
	v_pk_add_f32 v[34:35], v[42:43], v[34:35]
	v_pk_add_f32 v[44:45], v[58:59], v[60:61]
	v_pk_add_f32 v[34:35], v[34:35], v[40:41]
	s_nop 1
	v_permlane16_swap_b32_e32 v228, v230
	v_permlane16_swap_b32_e32 v229, v231
	v_lshl_add_u64 v[236:237], v[50:51], 0, v[238:239]
	global_store_dwordx4 v[236:237], v[228:231], off
	v_pk_add_f32 v[34:35], v[34:35], v[44:45]
	ds_bpermute_b32 v40, v156, v34
	ds_bpermute_b32 v41, v156, v35
	v_cvt_pk_bf16_f32 v232, v36, v37
	v_cvt_pk_bf16_f32 v233, v38, v39
	v_cvt_pk_bf16_f32 v234, v54, v55
	s_waitcnt lgkmcnt(0)
	v_pk_add_f32 v[32:33], v[34:35], v[40:41]
	ds_bpermute_b32 v34, v116, v32
	ds_bpermute_b32 v35, v116, v33
	v_cvt_pk_bf16_f32 v235, v52, v53
	s_nop 1
	v_permlane16_swap_b32_e32 v232, v234
	v_permlane16_swap_b32_e32 v233, v235
	global_store_dwordx4 v[236:237], v[232:235], off offset:256
	s_and_saveexec_b64 s[26:27], s[6:7]
	s_cbranch_execz .LBB0_283
	s_waitcnt lgkmcnt(0)
	v_pk_add_f32 v[32:33], v[32:33], v[34:35]
	v_lshlrev_b64 v[34:35], 7, v[48:49]
	v_lshl_add_u64 v[34:35], s[14:15], 0, v[34:35]
	v_lshl_add_u64 v[34:35], s[24:25], 2, v[34:35]
	global_store_dwordx2 v[34:35], v[32:33], off
; #define GASP __attribute__((address_space(1)))
;     __device__ __forceinline__ void operator()(Acc& acc, const Unit& u, int wr, int wc, int fr, int fq, LAS unsigned char* lds) const {
;     ...
;                 const int rl = ai * HALF + wr * 64 + m * 16 + fr, row = u.pm * BM + rl;
;                 const float* rp = (row < split) ? res0 + (size_t)row * D : res1 + (size_t)(row - split) * D;
;                 float* op = out + (size_t)row * D;
;                 f32x2 st = (f32x2){0.f, 1.f}; if (STp) st = SL[rl];
;                 float s = 0.f, q = 0.f;
; #pragma unroll
;                 for (int bj = 0; bj < 2; ++bj)
; #pragma unroll
;                     for (int n = 0; n < 2; ++n) { const int c = col0 + bj * HALF + n * 16; f32x4 r;
;                         if (resb) { const u32x2 w = *(const GASP u32x2*)(resb + (size_t)row * D + c);
;                             r = (f32x4){__uint_as_float(w.x << 16), __uint_as_float(w.x & 0xffff0000u), __uint_as_float(w.y << 16), __uint_as_float(w.y & 0xffff0000u)}; }
;                         else r = *(const GASP f32x4*)(rp + c);
;                         if (STp) r = (r - st[0]) * st[1] * gg[bj][n] + bb[bj][n];
;                         const f32x4 o = r * ALPHA + acc[ai][bj][m][n] * scale;
;                         if (out) *(GASP f32x4*)(op + c) = o;
;                         if (ob) { u32x2 w; w.x = pk2(o[0], o[1]); w.y = pk2(o[2], o[3]); *(GASP u32x2*)(ob + (size_t)row * D + c) = w; }
;                         s += (o[0] + o[1]) + (o[2] + o[3]); q += (o[0] * o[0] + o[1] * o[1]) + (o[2] * o[2] + o[3] * o[3]); }
;                 if (STn) { s += __shfl_xor(s, 16); s += __shfl_xor(s, 32); q += __shfl_xor(q, 16); q += __shfl_xor(q, 32);
;                     if (fq == 0) *(GASP f32x2*)(STn + (size_t)row * 32 + (u.pn * 4 + wc) * 2) = (f32x2){s, q}; }
.LBB0_283:
	s_or_b64 exec, exec, s[26:27]
	v_add_u32_e32 v32, 0xa0, v144
	v_ashrrev_i32_e32 v33, 31, v32
	v_cmp_gt_i32_e32 vcc, s41, v32
	s_nop 1
	v_cndmask_b32_e32 v33, 0, v33, vcc
	s_waitcnt lgkmcnt(0)
	v_lshlrev_b64 v[34:35], 11, v[32:33]
	v_lshl_add_u64 v[34:35], s[42:43], 0, v[34:35]
	v_lshl_add_u64 v[34:35], v[142:143], 1, v[34:35]
	global_load_dwordx2 v[36:37], v[34:35], off
	global_load_dwordx2 v[38:39], v[34:35], off offset:32
	global_load_dwordx2 v[40:41], v[34:35], off offset:256
	global_load_dwordx2 v[42:43], v[34:35], off offset:288
	s_waitcnt vmcnt(3)
	v_lshlrev_b32_e32 v44, 16, v36
	s_waitcnt vmcnt(2)
	v_lshlrev_b32_e32 v46, 16, v38
	v_and_b32_e32 v47, 0xffff0000, v38
	v_lshlrev_b32_e32 v38, 16, v39
	v_and_b32_e32 v39, 0xffff0000, v39
	v_and_b32_e32 v45, 0xffff0000, v36
	v_lshlrev_b32_e32 v36, 16, v37
	v_and_b32_e32 v37, 0xffff0000, v37
	s_waitcnt vmcnt(1)
	v_lshlrev_b32_e32 v48, 16, v40
	v_and_b32_e32 v49, 0xffff0000, v40
	v_pk_mul_f32 v[38:39], v[38:39], s[20:21] op_sel_hi:[1,0]
	v_lshlrev_b32_e32 v40, 16, v41
	v_and_b32_e32 v41, 0xffff0000, v41
	s_waitcnt vmcnt(0)
	v_lshlrev_b32_e32 v50, 16, v42
	v_and_b32_e32 v51, 0xffff0000, v42
	v_lshlrev_b32_e32 v42, 16, v43
	v_and_b32_e32 v43, 0xffff0000, v43
	v_pk_mul_f32 v[44:45], v[44:45], s[20:21] op_sel_hi:[1,0]
	v_pk_mul_f32 v[36:37], v[36:37], s[20:21] op_sel_hi:[1,0]
	v_pk_mul_f32 v[46:47], v[46:47], s[20:21] op_sel_hi:[1,0]
	v_pk_mul_f32 v[48:49], v[48:49], s[20:21] op_sel_hi:[1,0]
	v_pk_fma_f32 v[26:27], v[26:27], 0.5, v[38:39] op_sel_hi:[1,0,1]
	v_pk_mul_f32 v[40:41], v[40:41], s[20:21] op_sel_hi:[1,0]
	v_pk_mul_f32 v[50:51], v[50:51], s[20:21] op_sel_hi:[1,0]
	v_pk_mul_f32 v[42:43], v[42:43], s[20:21] op_sel_hi:[1,0]
	v_pk_fma_f32 v[30:31], v[30:31], 0.5, v[36:37] op_sel_hi:[1,0,1]
	v_pk_fma_f32 v[28:29], v[28:29], 0.5, v[44:45] op_sel_hi:[1,0,1]
	v_pk_fma_f32 v[24:25], v[24:25], 0.5, v[46:47] op_sel_hi:[1,0,1]
	v_pk_fma_f32 v[20:21], v[20:21], 0.5, v[48:49] op_sel_hi:[1,0,1]
	v_mul_f32_e32 v48, v26, v26
	v_pk_fma_f32 v[22:23], v[22:23], 0.5, v[40:41] op_sel_hi:[1,0,1]
	v_pk_fma_f32 v[36:37], v[18:19], 0.5, v[42:43] op_sel_hi:[1,0,1]
	v_pk_fma_f32 v[38:39], v[16:17], 0.5, v[50:51] op_sel_hi:[1,0,1]
	v_cvt_pk_bf16_f32 v228, v28, v29
	v_cvt_pk_bf16_f32 v229, v30, v31
	v_add_f32_e32 v18, v28, v29
	v_add_f32_e32 v40, v30, v31
	v_mul_f32_e32 v43, v28, v28
	v_mul_f32_e32 v29, v29, v29
	v_mul_f32_e32 v45, v30, v30
	v_mul_f32_e32 v31, v31, v31
	v_cvt_pk_bf16_f32 v230, v24, v25
	v_mul_f32_e32 v19, v24, v24
	v_mul_f32_e32 v41, v25, v25
	v_mov_b32_e32 v42, v24
	v_mov_b32_e32 v28, v25
	v_mov_b32_e32 v44, v26
	v_mov_b32_e32 v30, v27
	v_pk_fma_f32 v[24:25], v[26:27], v[26:27], v[48:49] op_sel_hi:[1,1,0]
	v_cvt_pk_bf16_f32 v231, v26, v27
	v_mul_f32_e32 v51, v20, v20
	v_mul_f32_e32 v53, v21, v21
	v_mul_f32_e32 v55, v22, v22
	v_mul_f32_e32 v57, v23, v23
	v_mov_b32_e32 v50, v20
	v_mov_b32_e32 v52, v21
	v_mov_b32_e32 v54, v22
	v_mov_b32_e32 v56, v23
	v_pk_add_f32 v[26:27], v[42:43], v[28:29]
	v_pk_add_f32 v[28:29], v[44:45], v[30:31]
	v_pk_add_f32 v[18:19], v[18:19], v[40:41]
	v_mov_b32_e32 v133, v25
	v_mul_f32_e32 v59, v38, v38
	v_mul_f32_e32 v61, v39, v39
	v_mul_f32_e32 v63, v36, v36
	v_mul_f32_e32 v65, v37, v37
	v_mov_b32_e32 v58, v38
	v_mov_b32_e32 v60, v39
	v_mov_b32_e32 v62, v36
	v_mov_b32_e32 v64, v37
	v_pk_add_f32 v[30:31], v[50:51], v[52:53]
	v_pk_add_f32 v[40:41], v[54:55], v[56:57]
	v_pk_add_f32 v[26:27], v[26:27], v[28:29]
	v_pk_add_f32 v[18:19], v[18:19], v[132:133]
	v_pk_add_f32 v[42:43], v[58:59], v[60:61]
	v_pk_add_f32 v[44:45], v[62:63], v[64:65]
	v_pk_add_f32 v[24:25], v[30:31], v[40:41]
	v_pk_add_f32 v[18:19], v[26:27], v[18:19]
	v_pk_add_f32 v[28:29], v[42:43], v[44:45]
	v_pk_add_f32 v[18:19], v[18:19], v[24:25]
	s_nop 1
	v_permlane16_swap_b32_e32 v228, v230
	v_permlane16_swap_b32_e32 v229, v231
	v_lshl_add_u64 v[236:237], v[34:35], 0, v[238:239]
	global_store_dwordx4 v[236:237], v[228:231], off
	v_pk_add_f32 v[18:19], v[18:19], v[28:29]
	ds_bpermute_b32 v24, v156, v18
	ds_bpermute_b32 v25, v156, v19
	v_cvt_pk_bf16_f32 v232, v20, v21
	v_cvt_pk_bf16_f32 v233, v22, v23
	v_cvt_pk_bf16_f32 v234, v38, v39
	s_waitcnt lgkmcnt(0)
	v_pk_add_f32 v[16:17], v[18:19], v[24:25]
	ds_bpermute_b32 v18, v116, v16
	ds_bpermute_b32 v19, v116, v17
	v_cvt_pk_bf16_f32 v235, v36, v37
	s_nop 1
	v_permlane16_swap_b32_e32 v232, v234
	v_permlane16_swap_b32_e32 v233, v235
	global_store_dwordx4 v[236:237], v[232:235], off offset:256
	s_and_saveexec_b64 s[26:27], s[6:7]
	s_cbranch_execz .LBB0_285
	s_waitcnt lgkmcnt(0)
	v_pk_add_f32 v[16:17], v[16:17], v[18:19]
	v_lshlrev_b64 v[18:19], 7, v[32:33]
	v_lshl_add_u64 v[18:19], s[14:15], 0, v[18:19]
	v_lshl_add_u64 v[18:19], s[24:25], 2, v[18:19]
	global_store_dwordx2 v[18:19], v[16:17], off
; #define GASP __attribute__((address_space(1)))
;     __device__ __forceinline__ void operator()(Acc& acc, const Unit& u, int wr, int wc, int fr, int fq, LAS unsigned char* lds) const {
;     ...
;                 const int rl = ai * HALF + wr * 64 + m * 16 + fr, row = u.pm * BM + rl;
;                 const float* rp = (row < split) ? res0 + (size_t)row * D : res1 + (size_t)(row - split) * D;
;                 float* op = out + (size_t)row * D;
;                 f32x2 st = (f32x2){0.f, 1.f}; if (STp) st = SL[rl];
;                 float s = 0.f, q = 0.f;
; #pragma unroll
;                 for (int bj = 0; bj < 2; ++bj)
; #pragma unroll
;                     for (int n = 0; n < 2; ++n) { const int c = col0 + bj * HALF + n * 16; f32x4 r;
;                         if (resb) { const u32x2 w = *(const GASP u32x2*)(resb + (size_t)row * D + c);
;                             r = (f32x4){__uint_as_float(w.x << 16), __uint_as_float(w.x & 0xffff0000u), __uint_as_float(w.y << 16), __uint_as_float(w.y & 0xffff0000u)}; }
;                         else r = *(const GASP f32x4*)(rp + c);
;                         if (STp) r = (r - st[0]) * st[1] * gg[bj][n] + bb[bj][n];
;                         const f32x4 o = r * ALPHA + acc[ai][bj][m][n] * scale;
;                         if (out) *(GASP f32x4*)(op + c) = o;
;                         if (ob) { u32x2 w; w.x = pk2(o[0], o[1]); w.y = pk2(o[2], o[3]); *(GASP u32x2*)(ob + (size_t)row * D + c) = w; }
;                         s += (o[0] + o[1]) + (o[2] + o[3]); q += (o[0] * o[0] + o[1] * o[1]) + (o[2] * o[2] + o[3] * o[3]); }
;                 if (STn) { s += __shfl_xor(s, 16); s += __shfl_xor(s, 32); q += __shfl_xor(q, 16); q += __shfl_xor(q, 32);
;                     if (fq == 0) *(GASP f32x2*)(STn + (size_t)row * 32 + (u.pn * 4 + wc) * 2) = (f32x2){s, q}; }
.LBB0_285:
	s_or_b64 exec, exec, s[26:27]
	v_add_u32_e32 v16, 0xb0, v144
	v_ashrrev_i32_e32 v17, 31, v16
	v_cmp_gt_i32_e32 vcc, s41, v16
	s_nop 1
	v_cndmask_b32_e32 v17, 0, v17, vcc
	s_waitcnt lgkmcnt(0)
	v_lshlrev_b64 v[18:19], 11, v[16:17]
	v_lshl_add_u64 v[18:19], s[42:43], 0, v[18:19]
	v_lshl_add_u64 v[18:19], v[142:143], 1, v[18:19]
	global_load_dwordx2 v[20:21], v[18:19], off
	global_load_dwordx2 v[22:23], v[18:19], off offset:32
	global_load_dwordx2 v[24:25], v[18:19], off offset:256
	global_load_dwordx2 v[26:27], v[18:19], off offset:288
	s_waitcnt vmcnt(3)
	v_lshlrev_b32_e32 v28, 16, v20
	s_waitcnt vmcnt(2)
	v_lshlrev_b32_e32 v30, 16, v22
	v_and_b32_e32 v31, 0xffff0000, v22
	v_lshlrev_b32_e32 v22, 16, v23
	v_and_b32_e32 v23, 0xffff0000, v23
	v_and_b32_e32 v29, 0xffff0000, v20
	v_lshlrev_b32_e32 v20, 16, v21
	v_and_b32_e32 v21, 0xffff0000, v21
	s_waitcnt vmcnt(1)
	v_lshlrev_b32_e32 v32, 16, v24
	v_and_b32_e32 v33, 0xffff0000, v24
	v_pk_mul_f32 v[22:23], v[22:23], s[20:21] op_sel_hi:[1,0]
	v_lshlrev_b32_e32 v24, 16, v25
	v_and_b32_e32 v25, 0xffff0000, v25
	s_waitcnt vmcnt(0)
	v_lshlrev_b32_e32 v34, 16, v26
	v_and_b32_e32 v35, 0xffff0000, v26
	v_lshlrev_b32_e32 v26, 16, v27
	v_and_b32_e32 v27, 0xffff0000, v27
	v_pk_mul_f32 v[28:29], v[28:29], s[20:21] op_sel_hi:[1,0]
	v_pk_mul_f32 v[20:21], v[20:21], s[20:21] op_sel_hi:[1,0]
	v_pk_mul_f32 v[30:31], v[30:31], s[20:21] op_sel_hi:[1,0]
	v_pk_mul_f32 v[32:33], v[32:33], s[20:21] op_sel_hi:[1,0]
	v_pk_fma_f32 v[10:11], v[10:11], 0.5, v[22:23] op_sel_hi:[1,0,1]
	v_pk_mul_f32 v[24:25], v[24:25], s[20:21] op_sel_hi:[1,0]
	v_pk_mul_f32 v[34:35], v[34:35], s[20:21] op_sel_hi:[1,0]
	v_pk_mul_f32 v[26:27], v[26:27], s[20:21] op_sel_hi:[1,0]
	v_pk_fma_f32 v[14:15], v[14:15], 0.5, v[20:21] op_sel_hi:[1,0,1]
	v_pk_fma_f32 v[12:13], v[12:13], 0.5, v[28:29] op_sel_hi:[1,0,1]
	v_pk_fma_f32 v[8:9], v[8:9], 0.5, v[30:31] op_sel_hi:[1,0,1]
	v_pk_fma_f32 v[4:5], v[4:5], 0.5, v[32:33] op_sel_hi:[1,0,1]
	v_mul_f32_e32 v32, v10, v10
	v_pk_fma_f32 v[6:7], v[6:7], 0.5, v[24:25] op_sel_hi:[1,0,1]
	v_pk_fma_f32 v[20:21], v[2:3], 0.5, v[26:27] op_sel_hi:[1,0,1]
	v_pk_fma_f32 v[22:23], v[0:1], 0.5, v[34:35] op_sel_hi:[1,0,1]
	v_cvt_pk_bf16_f32 v228, v12, v13
	v_cvt_pk_bf16_f32 v229, v14, v15
	v_add_f32_e32 v2, v12, v13
	v_add_f32_e32 v24, v14, v15
	v_mul_f32_e32 v27, v12, v12
	v_mul_f32_e32 v13, v13, v13
	v_mul_f32_e32 v29, v14, v14
	v_mul_f32_e32 v15, v15, v15
	v_cvt_pk_bf16_f32 v230, v8, v9
	v_mul_f32_e32 v3, v8, v8
	v_mul_f32_e32 v25, v9, v9
	v_mov_b32_e32 v26, v8
	v_mov_b32_e32 v12, v9
	v_mov_b32_e32 v28, v10
	v_mov_b32_e32 v14, v11
	v_pk_fma_f32 v[8:9], v[10:11], v[10:11], v[32:33] op_sel_hi:[1,1,0]
	v_cvt_pk_bf16_f32 v231, v10, v11
	v_mul_f32_e32 v35, v4, v4
	v_mul_f32_e32 v37, v5, v5
	v_mul_f32_e32 v39, v6, v6
	v_mul_f32_e32 v41, v7, v7
	v_mov_b32_e32 v34, v4
	v_mov_b32_e32 v36, v5
	v_mov_b32_e32 v38, v6
	v_mov_b32_e32 v40, v7
	v_pk_add_f32 v[10:11], v[26:27], v[12:13]
	v_pk_add_f32 v[12:13], v[28:29], v[14:15]
	v_pk_add_f32 v[2:3], v[2:3], v[24:25]
	v_mov_b32_e32 v133, v9
	v_mul_f32_e32 v43, v22, v22
	v_mul_f32_e32 v45, v23, v23
	v_mul_f32_e32 v47, v20, v20
	v_mul_f32_e32 v49, v21, v21
	v_mov_b32_e32 v42, v22
	v_mov_b32_e32 v44, v23
	v_mov_b32_e32 v46, v20
	v_mov_b32_e32 v48, v21
	v_pk_add_f32 v[14:15], v[34:35], v[36:37]
	v_pk_add_f32 v[24:25], v[38:39], v[40:41]
	v_pk_add_f32 v[10:11], v[10:11], v[12:13]
	v_pk_add_f32 v[2:3], v[2:3], v[132:133]
	v_pk_add_f32 v[26:27], v[42:43], v[44:45]
	v_pk_add_f32 v[28:29], v[46:47], v[48:49]
	v_pk_add_f32 v[8:9], v[14:15], v[24:25]
	v_pk_add_f32 v[2:3], v[10:11], v[2:3]
	v_pk_add_f32 v[12:13], v[26:27], v[28:29]
	v_pk_add_f32 v[2:3], v[2:3], v[8:9]
	s_nop 1
	v_permlane16_swap_b32_e32 v228, v230
	v_permlane16_swap_b32_e32 v229, v231
	v_lshl_add_u64 v[236:237], v[18:19], 0, v[238:239]
	global_store_dwordx4 v[236:237], v[228:231], off
	v_pk_add_f32 v[2:3], v[2:3], v[12:13]
	ds_bpermute_b32 v8, v156, v2
	ds_bpermute_b32 v9, v156, v3
	v_cvt_pk_bf16_f32 v232, v4, v5
	v_cvt_pk_bf16_f32 v233, v6, v7
	v_cvt_pk_bf16_f32 v234, v22, v23
	s_waitcnt lgkmcnt(0)
	v_pk_add_f32 v[0:1], v[2:3], v[8:9]
	ds_bpermute_b32 v2, v116, v0
	ds_bpermute_b32 v3, v116, v1
	v_cvt_pk_bf16_f32 v235, v20, v21
	s_nop 1
	v_permlane16_swap_b32_e32 v232, v234
	v_permlane16_swap_b32_e32 v233, v235
	global_store_dwordx4 v[236:237], v[232:235], off offset:256
	s_and_saveexec_b64 s[26:27], s[6:7]
	s_cbranch_execz .LBB0_287
	s_waitcnt lgkmcnt(0)
	v_pk_add_f32 v[0:1], v[0:1], v[2:3]
	v_lshlrev_b64 v[2:3], 7, v[16:17]
	v_lshl_add_u64 v[2:3], s[14:15], 0, v[2:3]
	v_lshl_add_u64 v[2:3], s[24:25], 2, v[2:3]
	global_store_dwordx2 v[2:3], v[0:1], off

; #define LAS __attribute__((address_space(3)))
; #define GASP __attribute__((address_space(1)))
; __device__ __forceinline__ void row_stats_table(LAS unsigned char* lds, const float* ST, int pm) {
;     ...
;     if (tid < 256) { const GASP f32x4* sp = (const GASP f32x4*)(ST + (size_t)(pm * BM + tid) * 32); float s = 0.f, q = 0.f;
; #pragma unroll
;         for (int i = 0; i < 8; ++i) { const f32x4 v = sp[i]; s += v[0] + v[2]; q += v[1] + v[3]; }
;         const float mu = s * (1.f / D), var = q * (1.f / D) - mu * mu;
;         ((LAS f32x2*)(lds + SL_OFF))[tid] = (f32x2){mu, 1.f / sqrtf(var + LN_EPS)}; }
;     asm volatile("s_waitcnt lgkmcnt(0)" ::: "memory"); __builtin_amdgcn_s_barrier(); asm volatile("" ::: "memory");
; }
;     __device__ __forceinline__ void operator()(Acc& acc, const Unit& u, int wr, int wc, int fr, int fq, LAS unsigned char* lds) const {
;     ...
;         if (STp) row_stats_table(lds, STp, u.pm);
;         const LAS f32x2* SL = (const LAS f32x2*)(lds + SL_OFF);
;         f32x4 gg[2][2], bb[2][2];
;         if (STp) {
; #pragma unroll
;             for (int bj = 0; bj < 2; ++bj)
; #pragma unroll
;                 for (int n = 0; n < 2; ++n) { gg[bj][n] = *(const GASP f32x4*)(gam + col0 + bj * HALF + n * 16); bb[bj][n] = *(const GASP f32x4*)(bet + col0 + bj * HALF + n * 16); }
;         }
; #pragma unroll
;         for (int ai = 0; ai < 2; ++ai)
; #pragma unroll
;             for (int m = 0; m < 4; ++m) {
;                 const int rl = ai * HALF + wr * 64 + m * 16 + fr, row = u.pm * BM + rl;
;                 const float* rp = (row < split) ? res0 + (size_t)row * D : res1 + (size_t)(row - split) * D;
;                 float* op = out + (size_t)row * D;
;                 f32x2 st = (f32x2){0.f, 1.f}; if (STp) st = SL[rl];
;                 float s = 0.f, q = 0.f;
; #pragma unroll
;                 for (int bj = 0; bj < 2; ++bj)
; #pragma unroll
;                     for (int n = 0; n < 2; ++n) { const int c = col0 + bj * HALF + n * 16; f32x4 r;
;                         if (resb) { const u32x2 w = *(const GASP u32x2*)(resb + (size_t)row * D + c);
;                             r = (f32x4){__uint_as_float(w.x << 16), __uint_as_float(w.x & 0xffff0000u), __uint_as_float(w.y << 16), __uint_as_float(w.y & 0xffff0000u)}; }
;                         else r = *(const GASP f32x4*)(rp + c);
.LBB0_1648:
	v_mbcnt_lo_u32_b32 v250, -1, 0
	v_mbcnt_hi_u32_b32 v250, -1, v250
	v_bfe_u32 v250, v250, 4, 1
	v_mul_u32_u24_e32 v250, 24, v250
	v_mov_b32_e32 v251, 0
	s_lshl_b32 s36, s61, 8
	s_and_saveexec_b64 s[34:35], s[6:7]
	s_cbranch_execz .LBB0_1650
	v_or_b32_e32 v76, s36, v208
	v_ashrrev_i32_e32 v77, 31, v76
	v_lshlrev_b64 v[76:77], 7, v[76:77]
	v_lshl_add_u64 v[136:137], s[46:47], 0, v[76:77]
	global_load_dwordx4 v[76:79], v[136:137], off
	global_load_dwordx4 v[80:83], v[136:137], off offset:16
	global_load_dwordx4 v[88:91], v[136:137], off offset:32
	global_load_dwordx4 v[92:95], v[136:137], off offset:48
	global_load_dwordx4 v[96:99], v[136:137], off offset:64
	global_load_dwordx4 v[100:103], v[136:137], off offset:80
	global_load_dwordx4 v[132:135], v[136:137], off offset:96
	s_nop 0
	global_load_dwordx4 v[136:139], v[136:137], off offset:112
	s_waitcnt vmcnt(0)
	v_pk_add_f32 v[76:77], v[76:77], v[78:79]
	v_pk_add_f32 v[78:79], v[80:81], v[82:83]
	v_pk_add_f32 v[76:77], v[76:77], 0 op_sel_hi:[1,0]
	v_pk_add_f32 v[80:81], v[88:89], v[90:91]
	v_pk_add_f32 v[76:77], v[76:77], v[78:79]
	v_pk_add_f32 v[82:83], v[92:93], v[94:95]
	v_pk_add_f32 v[76:77], v[76:77], v[80:81]
	v_pk_add_f32 v[88:89], v[96:97], v[98:99]
	v_pk_add_f32 v[76:77], v[76:77], v[82:83]
	v_pk_add_f32 v[90:91], v[100:101], v[102:103]
	v_pk_add_f32 v[76:77], v[76:77], v[88:89]
	v_pk_add_f32 v[92:93], v[132:133], v[134:135]
	v_pk_add_f32 v[76:77], v[76:77], v[90:91]
	v_pk_add_f32 v[94:95], v[136:137], v[138:139]
	v_pk_add_f32 v[76:77], v[76:77], v[92:93]
	s_nop 0
	v_pk_add_f32 v[76:77], v[76:77], v[94:95]
	s_nop 0
	v_pk_mul_f32 v[76:77], v[76:77], s[24:25] op_sel_hi:[1,0]
	s_nop 0
	v_fma_f32 v77, -v76, v76, v77
	v_add_f32_e32 v77, 0x3727c5ac, v77
	v_mul_f32_e32 v78, 0x4f800000, v77
	v_cmp_gt_f32_e32 vcc, s51, v77
	s_nop 1
	v_cndmask_b32_e32 v77, v77, v78, vcc
	v_sqrt_f32_e32 v78, v77
	s_nop 0
	v_add_u32_e32 v79, -1, v78
	v_add_u32_e32 v80, 1, v78
	v_fma_f32 v81, -v79, v78, v77
	v_fma_f32 v82, -v80, v78, v77
	v_cmp_ge_f32_e64 s[12:13], 0, v81
	s_nop 1
	v_cndmask_b32_e64 v78, v78, v79, s[12:13]
	v_cmp_lt_f32_e64 s[12:13], 0, v82
	s_nop 1
	v_cndmask_b32_e64 v78, v78, v80, s[12:13]
	v_mul_f32_e32 v79, 0x37800000, v78
	v_cndmask_b32_e32 v78, v78, v79, vcc
	v_cmp_class_f32_e32 vcc, v77, v216
	s_nop 1
	v_cndmask_b32_e32 v77, v78, v77, vcc
	v_div_scale_f32 v78, s[12:13], v77, v77, 1.0
	v_rcp_f32_e32 v79, v78
	v_div_scale_f32 v80, vcc, 1.0, v77, 1.0
	v_fma_f32 v81, -v78, v79, 1.0
	v_fmac_f32_e32 v79, v81, v79
	v_mul_f32_e32 v81, v80, v79
	v_fma_f32 v82, -v78, v81, v80
	v_fmac_f32_e32 v81, v82, v79
	v_fma_f32 v78, -v78, v81, v80
	v_div_fmas_f32 v78, v78, v79, v81
	v_div_fixup_f32 v77, v78, v77, 1.0
	ds_write_b64 v192, v[76:77]
.LBB0_1650:
	s_or_b64 exec, exec, s[34:35]
	v_add_u32_e32 v78, s36, v193
	v_ashrrev_i32_e32 v79, 31, v78
	v_cmp_gt_i32_e32 vcc, s56, v78
	v_lshl_or_b32 v76, s62, 8, v195
	v_ashrrev_i32_e32 v77, 31, v76
	v_cndmask_b32_e32 v79, 0, v79, vcc
	v_lshlrev_b64 v[78:79], 11, v[78:79]
	v_lshl_add_u64 v[78:79], s[42:43], 0, v[78:79]
	v_lshlrev_b64 v[172:173], 1, v[76:77]
	s_waitcnt lgkmcnt(0)
	s_barrier
	v_lshl_add_u64 v[176:177], v[78:79], 0, v[172:173]
	global_load_dwordx2 v[182:183], v[176:177], off
	global_load_dwordx2 v[184:185], v[176:177], off offset:32
	global_load_dwordx2 v[186:187], v[176:177], off offset:256
	v_lshlrev_b64 v[76:77], 2, v[76:77]
	v_lshl_add_u64 v[136:137], s[18:19], 0, v[76:77]
	v_lshl_add_u64 v[132:133], s[16:17], 0, v[76:77]
	global_load_dwordx4 v[96:99], v[136:137], off
	global_load_dwordx4 v[100:103], v[132:133], off
	global_load_dwordx4 v[88:91], v[132:133], off offset:64
	global_load_dwordx4 v[92:95], v[136:137], off offset:64
	global_load_dwordx4 v[76:79], v[132:133], off offset:512
	global_load_dwordx4 v[80:83], v[136:137], off offset:512
	v_add_u32_e32 v134, s36, v197
	global_load_dwordx2 v[190:191], v[176:177], off offset:288
	v_ashrrev_i32_e32 v135, 31, v134
	v_cmp_gt_i32_e32 vcc, s56, v134
	ds_read_b64 v[188:189], v196
	ds_read_b64 v[180:181], v198
	ds_read_b64 v[178:179], v200
	ds_read_b64 v[174:175], v202
	v_cndmask_b32_e32 v135, 0, v135, vcc
	v_lshlrev_b64 v[218:219], 11, v[134:135]
	global_load_dwordx4 v[132:135], v[132:133], off offset:576
	s_nop 0
	global_load_dwordx4 v[136:139], v[136:137], off offset:576
	v_lshl_add_u64 v[218:219], s[42:43], 0, v[218:219]
	v_lshl_add_u64 v[218:219], v[218:219], 0, v[172:173]
	global_load_dwordx2 v[220:221], v[218:219], off
	global_load_dwordx2 v[222:223], v[218:219], off offset:32
	s_waitcnt vmcnt(0)
	v_lshlrev_b32_e32 v217, 16, v182
	v_and_b32_e32 v224, 0xffff0000, v182
	v_lshlrev_b32_e32 v182, 16, v183
	v_and_b32_e32 v183, 0xffff0000, v183
	v_lshlrev_b32_e32 v230, 16, v184
	v_and_b32_e32 v231, 0xffff0000, v184
	v_lshlrev_b32_e32 v232, 16, v185
	v_and_b32_e32 v233, 0xffff0000, v185
	v_lshlrev_b32_e32 v234, 16, v186
	v_and_b32_e32 v235, 0xffff0000, v186
	v_lshlrev_b32_e32 v236, 16, v187
	v_and_b32_e32 v237, 0xffff0000, v187
	s_waitcnt lgkmcnt(3)
; #define GASP __attribute__((address_space(1)))
;     __device__ __forceinline__ void operator()(Acc& acc, const Unit& u, int wr, int wc, int fr, int fq, LAS unsigned char* lds) const {
;     ...
;                 const float* rp = (row < split) ? res0 + (size_t)row * D : res1 + (size_t)(row - split) * D;
;                 float* op = out + (size_t)row * D;
;                 f32x2 st = (f32x2){0.f, 1.f}; if (STp) st = SL[rl];
;                 float s = 0.f, q = 0.f;
; #pragma unroll
;                 for (int bj = 0; bj < 2; ++bj)
; #pragma unroll
;                     for (int n = 0; n < 2; ++n) { const int c = col0 + bj * HALF + n * 16; f32x4 r;
;                         if (resb) { const u32x2 w = *(const GASP u32x2*)(resb + (size_t)row * D + c);
;                             r = (f32x4){__uint_as_float(w.x << 16), __uint_as_float(w.x & 0xffff0000u), __uint_as_float(w.y << 16), __uint_as_float(w.y & 0xffff0000u)}; }
;                         else r = *(const GASP f32x4*)(rp + c);
;                         if (STp) r = (r - st[0]) * st[1] * gg[bj][n] + bb[bj][n];
;                         const f32x4 o = r * ALPHA + acc[ai][bj][m][n] * scale;
;                         if (out) *(GASP f32x4*)(op + c) = o;
;                         if (ob) { u32x2 w; w.x = pk2(o[0], o[1]); w.y = pk2(o[2], o[3]); *(GASP u32x2*)(ob + (size_t)row * D + c) = w; }
	v_sub_f32_e32 v183, v183, v188
	v_sub_f32_e32 v182, v182, v188
	v_sub_f32_e32 v185, v224, v188
	v_sub_f32_e32 v184, v217, v188
	v_sub_f32_e32 v187, v231, v188
	v_sub_f32_e32 v186, v230, v188
	v_sub_f32_e32 v225, v233, v188
	v_sub_f32_e32 v224, v232, v188
	v_pk_mul_f32 v[184:185], v[188:189], v[184:185] op_sel:[1,0]
	v_pk_mul_f32 v[182:183], v[188:189], v[182:183] op_sel:[1,0]
	v_pk_mul_f32 v[224:225], v[188:189], v[224:225] op_sel:[1,0]
	v_pk_mul_f32 v[186:187], v[188:189], v[186:187] op_sel:[1,0]
	v_pk_fma_f32 v[182:183], v[102:103], v[182:183], v[98:99]
	v_pk_fma_f32 v[184:185], v[100:101], v[184:185], v[96:97]
	v_pk_fma_f32 v[186:187], v[88:89], v[186:187], v[92:93]
	v_pk_fma_f32 v[224:225], v[90:91], v[224:225], v[94:95]
	v_pk_mul_f32 v[184:185], v[184:185], s[26:27] op_sel_hi:[1,0]
	v_pk_mul_f32 v[182:183], v[182:183], s[26:27] op_sel_hi:[1,0]
	v_cndmask_b32_e64 v225, v225, v233, s[8:9]
	v_cndmask_b32_e64 v224, v224, v232, s[8:9]
	v_cndmask_b32_e64 v187, v187, v231, s[8:9]
	v_cndmask_b32_e64 v186, v186, v230, s[8:9]
	v_sub_f32_e32 v229, v237, v188
	v_sub_f32_e32 v228, v236, v188
	v_pk_fma_f32 v[158:159], v[158:159], 0.5, v[182:183] op_sel_hi:[1,0,1]
	v_pk_fma_f32 v[156:157], v[156:157], 0.5, v[184:185] op_sel_hi:[1,0,1]
	v_pk_mul_f32 v[182:183], v[186:187], s[26:27] op_sel_hi:[1,0]
	v_pk_mul_f32 v[184:185], v[224:225], s[26:27] op_sel_hi:[1,0]
	v_pk_mul_f32 v[228:229], v[188:189], v[228:229] op_sel:[1,0]
	v_pk_fma_f32 v[154:155], v[154:155], 0.5, v[184:185] op_sel_hi:[1,0,1]
	v_pk_fma_f32 v[152:153], v[152:153], 0.5, v[182:183] op_sel_hi:[1,0,1]
	v_pk_fma_f32 v[228:229], v[78:79], v[228:229], v[82:83]
	v_cvt_pk_bf16_f32 v242, v152, v153
	v_cvt_pk_bf16_f32 v243, v154, v155
	v_cndmask_b32_e64 v153, v229, v237, s[8:9]
	v_cndmask_b32_e64 v152, v228, v236, s[8:9]
	v_pk_mul_f32 v[152:153], v[152:153], s[26:27] op_sel_hi:[1,0]
	v_sub_f32_e32 v227, v235, v188
	v_pk_fma_f32 v[150:151], v[150:151], 0.5, v[152:153] op_sel_hi:[1,0,1]
	global_load_dwordx2 v[152:153], v[218:219], off offset:256
	v_sub_f32_e32 v226, v234, v188
	v_pk_mul_f32 v[226:227], v[188:189], v[226:227] op_sel:[1,0]
	v_cvt_pk_bf16_f32 v240, v156, v157
	v_pk_fma_f32 v[226:227], v[76:77], v[226:227], v[80:81]
	v_cvt_pk_bf16_f32 v241, v158, v159
	v_cndmask_b32_e64 v155, v227, v235, s[8:9]
	v_cndmask_b32_e64 v154, v226, v234, s[8:9]
	v_pk_mul_f32 v[154:155], v[154:155], s[26:27] op_sel_hi:[1,0]
	s_nop 1
	v_permlane16_swap_b32_e32 v240, v242
	v_permlane16_swap_b32_e32 v241, v243
	v_lshl_add_u64 v[248:249], v[176:177], 0, v[250:251]
	global_store_dwordx4 v[248:249], v[240:243], off
	v_pk_fma_f32 v[148:149], v[148:149], 0.5, v[154:155] op_sel_hi:[1,0,1]
	v_lshlrev_b32_e32 v156, 16, v191
	v_and_b32_e32 v157, 0xffff0000, v191
	v_cvt_pk_bf16_f32 v244, v148, v149
	v_cvt_pk_bf16_f32 v245, v150, v151
	v_sub_f32_e32 v151, v157, v188
	v_sub_f32_e32 v150, v156, v188
	v_lshlrev_b32_e32 v154, 16, v190
	v_and_b32_e32 v155, 0xffff0000, v190
	v_pk_mul_f32 v[150:151], v[188:189], v[150:151] op_sel:[1,0]
	v_sub_f32_e32 v149, v155, v188
	v_sub_f32_e32 v148, v154, v188
	v_pk_fma_f32 v[150:151], v[134:135], v[150:151], v[138:139]
	v_pk_mul_f32 v[148:149], v[188:189], v[148:149] op_sel:[1,0]
	v_cndmask_b32_e64 v151, v151, v157, s[8:9]
	v_cndmask_b32_e64 v150, v150, v156, s[8:9]
	v_pk_fma_f32 v[148:149], v[132:133], v[148:149], v[136:137]
	v_pk_mul_f32 v[150:151], v[150:151], s[26:27] op_sel_hi:[1,0]
	v_cndmask_b32_e64 v149, v149, v155, s[8:9]
	v_cndmask_b32_e64 v148, v148, v154, s[8:9]
	v_pk_fma_f32 v[142:143], v[142:143], 0.5, v[150:151] op_sel_hi:[1,0,1]
	global_load_dwordx2 v[150:151], v[218:219], off offset:288
	v_pk_mul_f32 v[148:149], v[148:149], s[26:27] op_sel_hi:[1,0]
	s_nop 0
	v_pk_fma_f32 v[140:141], v[140:141], 0.5, v[148:149] op_sel_hi:[1,0,1]
	s_nop 0
	v_cvt_pk_bf16_f32 v246, v140, v141
	v_cvt_pk_bf16_f32 v247, v142, v143
	s_nop 1
	v_permlane16_swap_b32_e32 v244, v246
	v_permlane16_swap_b32_e32 v245, v247
	global_store_dwordx4 v[248:249], v[244:247], off offset:256
	v_lshlrev_b32_e32 v140, 16, v221
	v_and_b32_e32 v141, 0xffff0000, v221
	s_waitcnt lgkmcnt(2)
	v_sub_f32_e32 v141, v141, v180
	v_sub_f32_e32 v140, v140, v180
	v_pk_mul_f32 v[140:141], v[180:181], v[140:141] op_sel:[1,0]
	v_lshlrev_b32_e32 v142, 16, v220
	v_pk_fma_f32 v[148:149], v[102:103], v[140:141], v[98:99]
	v_add_u32_e32 v140, s36, v199
	v_ashrrev_i32_e32 v141, 31, v140
	v_cmp_gt_i32_e32 vcc, s56, v140
	v_and_b32_e32 v143, 0xffff0000, v220
	v_sub_f32_e32 v143, v143, v180
	v_cndmask_b32_e32 v141, 0, v141, vcc
	v_lshlrev_b64 v[140:141], 11, v[140:141]
	v_lshl_add_u64 v[140:141], s[42:43], 0, v[140:141]
	v_lshl_add_u64 v[140:141], v[140:141], 0, v[172:173]
	global_load_dwordx2 v[154:155], v[140:141], off
	v_sub_f32_e32 v142, v142, v180
	v_pk_mul_f32 v[142:143], v[180:181], v[142:143] op_sel:[1,0]
	v_pk_mul_f32 v[148:149], v[148:149], s[26:27] op_sel_hi:[1,0]
	v_pk_fma_f32 v[142:143], v[100:101], v[142:143], v[96:97]
	v_pk_fma_f32 v[146:147], v[146:147], 0.5, v[148:149] op_sel_hi:[1,0,1]
	v_pk_mul_f32 v[142:143], v[142:143], s[26:27] op_sel_hi:[1,0]
	v_lshlrev_b32_e32 v148, 16, v223
	v_and_b32_e32 v149, 0xffff0000, v223
	v_pk_fma_f32 v[142:143], v[144:145], 0.5, v[142:143] op_sel_hi:[1,0,1]
	v_sub_f32_e32 v145, v149, v180
	v_sub_f32_e32 v144, v148, v180
	v_cvt_pk_bf16_f32 v240, v142, v143
	v_cvt_pk_bf16_f32 v241, v146, v147
	v_lshlrev_b32_e32 v146, 16, v222
	v_and_b32_e32 v147, 0xffff0000, v222
	v_pk_mul_f32 v[144:145], v[180:181], v[144:145] op_sel:[1,0]
	v_sub_f32_e32 v143, v147, v180
	v_sub_f32_e32 v142, v146, v180
	v_pk_fma_f32 v[144:145], v[90:91], v[144:145], v[94:95]
	v_pk_mul_f32 v[142:143], v[180:181], v[142:143] op_sel:[1,0]
	v_cndmask_b32_e64 v145, v145, v149, s[8:9]
	v_cndmask_b32_e64 v144, v144, v148, s[8:9]
	v_pk_fma_f32 v[142:143], v[88:89], v[142:143], v[92:93]
	v_pk_mul_f32 v[144:145], v[144:145], s[26:27] op_sel_hi:[1,0]
	v_cndmask_b32_e64 v143, v143, v147, s[8:9]
	v_cndmask_b32_e64 v142, v142, v146, s[8:9]
	v_pk_fma_f32 v[130:131], v[130:131], 0.5, v[144:145] op_sel_hi:[1,0,1]
	global_load_dwordx2 v[144:145], v[140:141], off offset:32
	v_pk_mul_f32 v[142:143], v[142:143], s[26:27] op_sel_hi:[1,0]
	s_waitcnt vmcnt(5)
; #define GASP __attribute__((address_space(1)))
;     __device__ __forceinline__ void operator()(Acc& acc, const Unit& u, int wr, int wc, int fr, int fq, LAS unsigned char* lds) const {
;     ...
;                 const float* rp = (row < split) ? res0 + (size_t)row * D : res1 + (size_t)(row - split) * D;
;                 float* op = out + (size_t)row * D;
;                 f32x2 st = (f32x2){0.f, 1.f}; if (STp) st = SL[rl];
;                 float s = 0.f, q = 0.f;
; #pragma unroll
;                 for (int bj = 0; bj < 2; ++bj)
; #pragma unroll
;                     for (int n = 0; n < 2; ++n) { const int c = col0 + bj * HALF + n * 16; f32x4 r;
;                         if (resb) { const u32x2 w = *(const GASP u32x2*)(resb + (size_t)row * D + c);
;                             r = (f32x4){__uint_as_float(w.x << 16), __uint_as_float(w.x & 0xffff0000u), __uint_as_float(w.y << 16), __uint_as_float(w.y & 0xffff0000u)}; }
;                         else r = *(const GASP f32x4*)(rp + c);
;                         if (STp) r = (r - st[0]) * st[1] * gg[bj][n] + bb[bj][n];
;                         const f32x4 o = r * ALPHA + acc[ai][bj][m][n] * scale;
;                         if (out) *(GASP f32x4*)(op + c) = o;
;                         if (ob) { u32x2 w; w.x = pk2(o[0], o[1]); w.y = pk2(o[2], o[3]); *(GASP u32x2*)(ob + (size_t)row * D + c) = w; }
	v_lshlrev_b32_e32 v146, 16, v153
	v_pk_fma_f32 v[128:129], v[128:129], 0.5, v[142:143] op_sel_hi:[1,0,1]
	v_and_b32_e32 v147, 0xffff0000, v153
	v_cvt_pk_bf16_f32 v242, v128, v129
	v_cvt_pk_bf16_f32 v243, v130, v131
	v_sub_f32_e32 v131, v147, v180
	v_sub_f32_e32 v130, v146, v180
	v_pk_mul_f32 v[130:131], v[180:181], v[130:131] op_sel:[1,0]
	v_lshlrev_b32_e32 v142, 16, v152
	v_pk_fma_f32 v[130:131], v[78:79], v[130:131], v[82:83]
	v_and_b32_e32 v143, 0xffff0000, v152
	v_cndmask_b32_e64 v131, v131, v147, s[8:9]
	v_cndmask_b32_e64 v130, v130, v146, s[8:9]
	v_pk_mul_f32 v[130:131], v[130:131], s[26:27] op_sel_hi:[1,0]
	s_nop 1
	v_permlane16_swap_b32_e32 v240, v242
	v_permlane16_swap_b32_e32 v241, v243
	v_lshl_add_u64 v[248:249], v[218:219], 0, v[250:251]
	global_store_dwordx4 v[248:249], v[240:243], off
	v_pk_fma_f32 v[126:127], v[126:127], 0.5, v[130:131] op_sel_hi:[1,0,1]
	global_load_dwordx2 v[130:131], v[140:141], off offset:256
	v_sub_f32_e32 v129, v143, v180
	v_sub_f32_e32 v128, v142, v180
	v_pk_mul_f32 v[128:129], v[180:181], v[128:129] op_sel:[1,0]
	s_nop 0
	v_pk_fma_f32 v[128:129], v[76:77], v[128:129], v[80:81]
	s_nop 0
	v_cndmask_b32_e64 v129, v129, v143, s[8:9]
	v_cndmask_b32_e64 v128, v128, v142, s[8:9]
	v_pk_mul_f32 v[128:129], v[128:129], s[26:27] op_sel_hi:[1,0]
	s_waitcnt vmcnt(5)
	v_lshlrev_b32_e32 v142, 16, v151
	v_pk_fma_f32 v[124:125], v[124:125], 0.5, v[128:129] op_sel_hi:[1,0,1]
	v_and_b32_e32 v143, 0xffff0000, v151
	v_cvt_pk_bf16_f32 v244, v124, v125
	v_cvt_pk_bf16_f32 v245, v126, v127
	v_sub_f32_e32 v127, v143, v180
	v_sub_f32_e32 v126, v142, v180
	v_pk_mul_f32 v[126:127], v[180:181], v[126:127] op_sel:[1,0]
	v_lshlrev_b32_e32 v128, 16, v150
	v_pk_fma_f32 v[126:127], v[134:135], v[126:127], v[138:139]
	v_and_b32_e32 v129, 0xffff0000, v150
	v_cndmask_b32_e64 v127, v127, v143, s[8:9]
	v_cndmask_b32_e64 v126, v126, v142, s[8:9]
	v_pk_mul_f32 v[126:127], v[126:127], s[26:27] op_sel_hi:[1,0]
	v_sub_f32_e32 v125, v129, v180
	v_sub_f32_e32 v124, v128, v180
	v_pk_fma_f32 v[118:119], v[118:119], 0.5, v[126:127] op_sel_hi:[1,0,1]
	global_load_dwordx2 v[126:127], v[140:141], off offset:288
	v_pk_mul_f32 v[124:125], v[180:181], v[124:125] op_sel:[1,0]
	s_nop 0
	v_pk_fma_f32 v[124:125], v[132:133], v[124:125], v[136:137]
	s_nop 0
	v_cndmask_b32_e64 v125, v125, v129, s[8:9]
	v_cndmask_b32_e64 v124, v124, v128, s[8:9]
	v_pk_mul_f32 v[124:125], v[124:125], s[26:27] op_sel_hi:[1,0]
	s_nop 0
	v_pk_fma_f32 v[116:117], v[116:117], 0.5, v[124:125] op_sel_hi:[1,0,1]
	s_nop 0
	v_cvt_pk_bf16_f32 v246, v116, v117
	v_cvt_pk_bf16_f32 v247, v118, v119
	s_nop 1
	v_permlane16_swap_b32_e32 v244, v246
	v_permlane16_swap_b32_e32 v245, v247
	global_store_dwordx4 v[248:249], v[244:247], off offset:256
	s_waitcnt vmcnt(5)
	v_lshlrev_b32_e32 v116, 16, v155
	v_and_b32_e32 v117, 0xffff0000, v155
	s_waitcnt lgkmcnt(1)
	v_sub_f32_e32 v117, v117, v178
	v_sub_f32_e32 v116, v116, v178
	v_pk_mul_f32 v[116:117], v[178:179], v[116:117] op_sel:[1,0]
	v_lshlrev_b32_e32 v118, 16, v154
	v_pk_fma_f32 v[124:125], v[102:103], v[116:117], v[98:99]
	v_add_u32_e32 v116, s36, v201
	v_ashrrev_i32_e32 v117, 31, v116
	v_cmp_gt_i32_e32 vcc, s56, v116
	v_and_b32_e32 v119, 0xffff0000, v154
	v_sub_f32_e32 v119, v119, v178
	v_cndmask_b32_e32 v117, 0, v117, vcc
	v_lshlrev_b64 v[116:117], 11, v[116:117]
	v_sub_f32_e32 v118, v118, v178
	v_lshl_add_u64 v[116:117], s[42:43], 0, v[116:117]
	v_pk_mul_f32 v[118:119], v[178:179], v[118:119] op_sel:[1,0]
	v_lshl_add_u64 v[116:117], v[116:117], 0, v[172:173]
	v_pk_fma_f32 v[118:119], v[100:101], v[118:119], v[96:97]
	global_load_dwordx2 v[128:129], v[116:117], off
	v_pk_mul_f32 v[124:125], v[124:125], s[26:27] op_sel_hi:[1,0]
	v_pk_mul_f32 v[118:119], v[118:119], s[26:27] op_sel_hi:[1,0]
	v_pk_fma_f32 v[122:123], v[122:123], 0.5, v[124:125] op_sel_hi:[1,0,1]
	s_waitcnt vmcnt(5)
	v_lshlrev_b32_e32 v124, 16, v145
	v_and_b32_e32 v125, 0xffff0000, v145
	v_pk_fma_f32 v[118:119], v[120:121], 0.5, v[118:119] op_sel_hi:[1,0,1]
	v_sub_f32_e32 v121, v125, v178
	v_sub_f32_e32 v120, v124, v178
	v_cvt_pk_bf16_f32 v240, v118, v119
	v_cvt_pk_bf16_f32 v241, v122, v123
	v_lshlrev_b32_e32 v122, 16, v144
	v_and_b32_e32 v123, 0xffff0000, v144
	v_pk_mul_f32 v[120:121], v[178:179], v[120:121] op_sel:[1,0]
	v_sub_f32_e32 v119, v123, v178
	v_sub_f32_e32 v118, v122, v178
	v_pk_fma_f32 v[120:121], v[90:91], v[120:121], v[94:95]
	v_pk_mul_f32 v[118:119], v[178:179], v[118:119] op_sel:[1,0]
	v_cndmask_b32_e64 v121, v121, v125, s[8:9]
	v_cndmask_b32_e64 v120, v120, v124, s[8:9]
	v_pk_fma_f32 v[118:119], v[88:89], v[118:119], v[92:93]
	v_pk_mul_f32 v[120:121], v[120:121], s[26:27] op_sel_hi:[1,0]
	v_cndmask_b32_e64 v119, v119, v123, s[8:9]
	v_cndmask_b32_e64 v118, v118, v122, s[8:9]
	v_pk_fma_f32 v[114:115], v[114:115], 0.5, v[120:121] op_sel_hi:[1,0,1]
	global_load_dwordx2 v[120:121], v[116:117], off offset:32
	v_pk_mul_f32 v[118:119], v[118:119], s[26:27] op_sel_hi:[1,0]
	s_waitcnt vmcnt(4)
	v_lshlrev_b32_e32 v122, 16, v131
	v_pk_fma_f32 v[112:113], v[112:113], 0.5, v[118:119] op_sel_hi:[1,0,1]
	v_and_b32_e32 v123, 0xffff0000, v131
	v_cvt_pk_bf16_f32 v242, v112, v113
	v_cvt_pk_bf16_f32 v243, v114, v115
	v_sub_f32_e32 v115, v123, v178
	v_sub_f32_e32 v114, v122, v178
	v_pk_mul_f32 v[114:115], v[178:179], v[114:115] op_sel:[1,0]
	v_lshlrev_b32_e32 v118, 16, v130
	v_pk_fma_f32 v[114:115], v[78:79], v[114:115], v[82:83]
	v_and_b32_e32 v119, 0xffff0000, v130
	v_cndmask_b32_e64 v115, v115, v123, s[8:9]
	v_cndmask_b32_e64 v114, v114, v122, s[8:9]
	v_pk_mul_f32 v[114:115], v[114:115], s[26:27] op_sel_hi:[1,0]
	s_nop 1
	v_permlane16_swap_b32_e32 v240, v242
	v_permlane16_swap_b32_e32 v241, v243
	v_lshl_add_u64 v[248:249], v[140:141], 0, v[250:251]
	global_store_dwordx4 v[248:249], v[240:243], off
	v_pk_fma_f32 v[110:111], v[110:111], 0.5, v[114:115] op_sel_hi:[1,0,1]
	global_load_dwordx2 v[114:115], v[116:117], off offset:256
	v_sub_f32_e32 v113, v119, v178
	v_sub_f32_e32 v112, v118, v178
	v_pk_mul_f32 v[112:113], v[178:179], v[112:113] op_sel:[1,0]
	s_nop 0
	v_pk_fma_f32 v[112:113], v[76:77], v[112:113], v[80:81]
	s_nop 0
	v_cndmask_b32_e64 v113, v113, v119, s[8:9]
	v_cndmask_b32_e64 v112, v112, v118, s[8:9]
	v_pk_mul_f32 v[112:113], v[112:113], s[26:27] op_sel_hi:[1,0]
	s_waitcnt vmcnt(5)
; #define GASP __attribute__((address_space(1)))
;     __device__ __forceinline__ void operator()(Acc& acc, const Unit& u, int wr, int wc, int fr, int fq, LAS unsigned char* lds) const {
;     ...
;                 const float* rp = (row < split) ? res0 + (size_t)row * D : res1 + (size_t)(row - split) * D;
;                 float* op = out + (size_t)row * D;
;                 f32x2 st = (f32x2){0.f, 1.f}; if (STp) st = SL[rl];
;                 float s = 0.f, q = 0.f;
; #pragma unroll
;                 for (int bj = 0; bj < 2; ++bj)
; #pragma unroll
;                     for (int n = 0; n < 2; ++n) { const int c = col0 + bj * HALF + n * 16; f32x4 r;
;                         if (resb) { const u32x2 w = *(const GASP u32x2*)(resb + (size_t)row * D + c);
;                             r = (f32x4){__uint_as_float(w.x << 16), __uint_as_float(w.x & 0xffff0000u), __uint_as_float(w.y << 16), __uint_as_float(w.y & 0xffff0000u)}; }
;                         else r = *(const GASP f32x4*)(rp + c);
;                         if (STp) r = (r - st[0]) * st[1] * gg[bj][n] + bb[bj][n];
;                         const f32x4 o = r * ALPHA + acc[ai][bj][m][n] * scale;
;                         if (out) *(GASP f32x4*)(op + c) = o;
;                         if (ob) { u32x2 w; w.x = pk2(o[0], o[1]); w.y = pk2(o[2], o[3]); *(GASP u32x2*)(ob + (size_t)row * D + c) = w; }
	v_lshlrev_b32_e32 v118, 16, v127
	v_pk_fma_f32 v[108:109], v[108:109], 0.5, v[112:113] op_sel_hi:[1,0,1]
	v_and_b32_e32 v119, 0xffff0000, v127
	v_cvt_pk_bf16_f32 v244, v108, v109
	v_cvt_pk_bf16_f32 v245, v110, v111
	v_sub_f32_e32 v111, v119, v178
	v_sub_f32_e32 v110, v118, v178
	v_pk_mul_f32 v[110:111], v[178:179], v[110:111] op_sel:[1,0]
	v_lshlrev_b32_e32 v112, 16, v126
	v_pk_fma_f32 v[110:111], v[134:135], v[110:111], v[138:139]
	v_and_b32_e32 v113, 0xffff0000, v126
	v_cndmask_b32_e64 v111, v111, v119, s[8:9]
	v_cndmask_b32_e64 v110, v110, v118, s[8:9]
	v_pk_mul_f32 v[110:111], v[110:111], s[26:27] op_sel_hi:[1,0]
	v_pk_fma_f32 v[106:107], v[106:107], 0.5, v[110:111] op_sel_hi:[1,0,1]
	global_load_dwordx2 v[110:111], v[116:117], off offset:288
	v_sub_f32_e32 v109, v113, v178
	v_sub_f32_e32 v108, v112, v178
	v_pk_mul_f32 v[108:109], v[178:179], v[108:109] op_sel:[1,0]
	s_nop 0
	v_pk_fma_f32 v[108:109], v[132:133], v[108:109], v[136:137]
	s_nop 0
	v_cndmask_b32_e64 v109, v109, v113, s[8:9]
	v_cndmask_b32_e64 v108, v108, v112, s[8:9]
	v_pk_mul_f32 v[108:109], v[108:109], s[26:27] op_sel_hi:[1,0]
	s_nop 0
	v_pk_fma_f32 v[104:105], v[104:105], 0.5, v[108:109] op_sel_hi:[1,0,1]
	s_nop 0
	v_cvt_pk_bf16_f32 v246, v104, v105
	v_cvt_pk_bf16_f32 v247, v106, v107
	s_nop 1
	v_permlane16_swap_b32_e32 v244, v246
	v_permlane16_swap_b32_e32 v245, v247
	global_store_dwordx4 v[248:249], v[244:247], off offset:256
	s_waitcnt vmcnt(5)
	v_lshlrev_b32_e32 v106, 16, v128
	v_and_b32_e32 v107, 0xffff0000, v128
	v_lshlrev_b32_e32 v104, 16, v129
	v_and_b32_e32 v105, 0xffff0000, v129
	s_waitcnt lgkmcnt(0)
	v_sub_f32_e32 v105, v105, v174
	v_sub_f32_e32 v104, v104, v174
	v_sub_f32_e32 v107, v107, v174
	v_sub_f32_e32 v106, v106, v174
	v_pk_mul_f32 v[106:107], v[174:175], v[106:107] op_sel:[1,0]
	v_pk_mul_f32 v[104:105], v[174:175], v[104:105] op_sel:[1,0]
	s_nop 0
	v_pk_fma_f32 v[108:109], v[102:103], v[104:105], v[98:99]
	v_pk_fma_f32 v[104:105], v[100:101], v[106:107], v[96:97]
	v_pk_mul_f32 v[108:109], v[108:109], s[26:27] op_sel_hi:[1,0]
	v_pk_mul_f32 v[106:107], v[104:105], s[26:27] op_sel_hi:[1,0]
	v_add_u32_e32 v104, s36, v203
	v_ashrrev_i32_e32 v105, 31, v104
	v_cmp_gt_i32_e32 vcc, s56, v104
	v_pk_fma_f32 v[86:87], v[86:87], 0.5, v[108:109] op_sel_hi:[1,0,1]
	v_pk_fma_f32 v[84:85], v[84:85], 0.5, v[106:107] op_sel_hi:[1,0,1]
	v_cndmask_b32_e32 v105, 0, v105, vcc
	v_lshlrev_b64 v[104:105], 11, v[104:105]
	v_cvt_pk_bf16_f32 v240, v84, v85
	v_cvt_pk_bf16_f32 v241, v86, v87
	s_waitcnt vmcnt(4)
	v_lshlrev_b32_e32 v106, 16, v120
	v_and_b32_e32 v107, 0xffff0000, v120
	v_lshlrev_b32_e32 v108, 16, v121
	v_and_b32_e32 v109, 0xffff0000, v121
	v_lshl_add_u64 v[104:105], s[42:43], 0, v[104:105]
	v_sub_f32_e32 v85, v107, v174
	v_sub_f32_e32 v84, v106, v174
	v_sub_f32_e32 v87, v109, v174
	v_sub_f32_e32 v86, v108, v174
	v_lshl_add_u64 v[104:105], v[104:105], 0, v[172:173]
	v_pk_mul_f32 v[86:87], v[174:175], v[86:87] op_sel:[1,0]
	v_pk_mul_f32 v[84:85], v[174:175], v[84:85] op_sel:[1,0]
	global_load_dwordx2 v[112:113], v[104:105], off
	v_pk_fma_f32 v[84:85], v[88:89], v[84:85], v[92:93]
	v_pk_fma_f32 v[86:87], v[90:91], v[86:87], v[94:95]
	v_cndmask_b32_e64 v85, v85, v107, s[8:9]
	v_cndmask_b32_e64 v87, v87, v109, s[8:9]
	v_cndmask_b32_e64 v86, v86, v108, s[8:9]
	v_cndmask_b32_e64 v84, v84, v106, s[8:9]
	v_pk_mul_f32 v[84:85], v[84:85], s[26:27] op_sel_hi:[1,0]
	v_pk_mul_f32 v[86:87], v[86:87], s[26:27] op_sel_hi:[1,0]
	v_pk_fma_f32 v[72:73], v[72:73], 0.5, v[84:85] op_sel_hi:[1,0,1]
	v_pk_fma_f32 v[74:75], v[74:75], 0.5, v[86:87] op_sel_hi:[1,0,1]
	v_cvt_pk_bf16_f32 v242, v72, v73
	v_cvt_pk_bf16_f32 v243, v74, v75
	s_nop 1
	v_permlane16_swap_b32_e32 v240, v242
	v_permlane16_swap_b32_e32 v241, v243
	v_lshl_add_u64 v[248:249], v[116:117], 0, v[250:251]
	global_store_dwordx4 v[248:249], v[240:243], off
	global_load_dwordx2 v[72:73], v[104:105], off offset:32
	s_waitcnt vmcnt(5)
	v_lshlrev_b32_e32 v86, 16, v114
	v_and_b32_e32 v87, 0xffff0000, v114
	v_lshlrev_b32_e32 v106, 16, v115
	v_and_b32_e32 v107, 0xffff0000, v115
	v_sub_f32_e32 v75, v87, v174
	v_sub_f32_e32 v74, v86, v174
	v_sub_f32_e32 v85, v107, v174
	v_sub_f32_e32 v84, v106, v174
	v_pk_mul_f32 v[84:85], v[174:175], v[84:85] op_sel:[1,0]
	v_pk_mul_f32 v[74:75], v[174:175], v[74:75] op_sel:[1,0]
	v_pk_fma_f32 v[84:85], v[78:79], v[84:85], v[82:83]
	v_pk_fma_f32 v[74:75], v[76:77], v[74:75], v[80:81]
	v_cndmask_b32_e64 v85, v85, v107, s[8:9]
	v_cndmask_b32_e64 v84, v84, v106, s[8:9]
	v_cndmask_b32_e64 v75, v75, v87, s[8:9]
	v_cndmask_b32_e64 v74, v74, v86, s[8:9]
	v_pk_mul_f32 v[74:75], v[74:75], s[26:27] op_sel_hi:[1,0]
	v_pk_mul_f32 v[84:85], v[84:85], s[26:27] op_sel_hi:[1,0]
	v_pk_fma_f32 v[68:69], v[68:69], 0.5, v[74:75] op_sel_hi:[1,0,1]
	v_pk_fma_f32 v[70:71], v[70:71], 0.5, v[84:85] op_sel_hi:[1,0,1]
	v_cvt_pk_bf16_f32 v244, v68, v69
	v_cvt_pk_bf16_f32 v245, v70, v71
	global_load_dwordx2 v[70:71], v[104:105], off offset:256
	s_waitcnt vmcnt(5)
; #define GASP __attribute__((address_space(1)))
;     __device__ __forceinline__ void operator()(Acc& acc, const Unit& u, int wr, int wc, int fr, int fq, LAS unsigned char* lds) const {
;     ...
;                 const float* rp = (row < split) ? res0 + (size_t)row * D : res1 + (size_t)(row - split) * D;
;                 float* op = out + (size_t)row * D;
;                 f32x2 st = (f32x2){0.f, 1.f}; if (STp) st = SL[rl];
;                 float s = 0.f, q = 0.f;
; #pragma unroll
;                 for (int bj = 0; bj < 2; ++bj)
; #pragma unroll
;                     for (int n = 0; n < 2; ++n) { const int c = col0 + bj * HALF + n * 16; f32x4 r;
;                         if (resb) { const u32x2 w = *(const GASP u32x2*)(resb + (size_t)row * D + c);
;                             r = (f32x4){__uint_as_float(w.x << 16), __uint_as_float(w.x & 0xffff0000u), __uint_as_float(w.y << 16), __uint_as_float(w.y & 0xffff0000u)}; }
;                         else r = *(const GASP f32x4*)(rp + c);
;                         if (STp) r = (r - st[0]) * st[1] * gg[bj][n] + bb[bj][n];
;                         const f32x4 o = r * ALPHA + acc[ai][bj][m][n] * scale;
;                         if (out) *(GASP f32x4*)(op + c) = o;
;                         if (ob) { u32x2 w; w.x = pk2(o[0], o[1]); w.y = pk2(o[2], o[3]); *(GASP u32x2*)(ob + (size_t)row * D + c) = w; }
	v_lshlrev_b32_e32 v84, 16, v110
	v_and_b32_e32 v85, 0xffff0000, v110
	v_sub_f32_e32 v69, v85, v174
	v_sub_f32_e32 v68, v84, v174
	v_pk_mul_f32 v[68:69], v[174:175], v[68:69] op_sel:[1,0]
	v_lshlrev_b32_e32 v86, 16, v111
	v_and_b32_e32 v87, 0xffff0000, v111
	v_pk_fma_f32 v[68:69], v[132:133], v[68:69], v[136:137]
	v_sub_f32_e32 v75, v87, v174
	v_sub_f32_e32 v74, v86, v174
	v_cndmask_b32_e64 v69, v69, v85, s[8:9]
	v_cndmask_b32_e64 v68, v68, v84, s[8:9]
	global_load_dwordx2 v[84:85], v[104:105], off offset:288
	v_pk_mul_f32 v[74:75], v[174:175], v[74:75] op_sel:[1,0]
	v_add_u32_e32 v108, s36, v205
	v_pk_fma_f32 v[74:75], v[134:135], v[74:75], v[138:139]
	v_ashrrev_i32_e32 v109, 31, v108
	v_cndmask_b32_e64 v75, v75, v87, s[8:9]
	v_cndmask_b32_e64 v74, v74, v86, s[8:9]
	v_cmp_gt_i32_e32 vcc, s56, v108
	v_pk_mul_f32 v[68:69], v[68:69], s[26:27] op_sel_hi:[1,0]
	v_pk_mul_f32 v[74:75], v[74:75], s[26:27] op_sel_hi:[1,0]
	v_cndmask_b32_e32 v109, 0, v109, vcc
	v_pk_fma_f32 v[66:67], v[66:67], 0.5, v[74:75] op_sel_hi:[1,0,1]
	v_pk_fma_f32 v[64:65], v[64:65], 0.5, v[68:69] op_sel_hi:[1,0,1]
	v_lshlrev_b64 v[108:109], 11, v[108:109]
	v_cvt_pk_bf16_f32 v246, v64, v65
	v_cvt_pk_bf16_f32 v247, v66, v67
	v_lshl_add_u64 v[108:109], s[42:43], 0, v[108:109]
	s_nop 1
	v_permlane16_swap_b32_e32 v244, v246
	v_permlane16_swap_b32_e32 v245, v247
	global_store_dwordx4 v[248:249], v[244:247], off offset:256
	v_lshl_add_u64 v[108:109], v[108:109], 0, v[172:173]
	ds_read_b64 v[74:75], v204
	ds_read_b64 v[66:67], v206
	ds_read_b64 v[64:65], v210
	ds_read_b64 v[68:69], v212
	global_load_dwordx2 v[110:111], v[108:109], off
	s_waitcnt vmcnt(6)
	v_lshlrev_b32_e32 v106, 16, v112
	v_and_b32_e32 v107, 0xffff0000, v112
	v_lshlrev_b32_e32 v86, 16, v113
	v_and_b32_e32 v87, 0xffff0000, v113
	s_waitcnt lgkmcnt(3)
	v_sub_f32_e32 v87, v87, v74
	v_sub_f32_e32 v86, v86, v74
	v_sub_f32_e32 v107, v107, v74
	v_sub_f32_e32 v106, v106, v74
	v_pk_mul_f32 v[106:107], v[74:75], v[106:107] op_sel:[1,0]
	v_pk_mul_f32 v[86:87], v[74:75], v[86:87] op_sel:[1,0]
	v_pk_fma_f32 v[106:107], v[100:101], v[106:107], v[96:97]
	v_pk_fma_f32 v[86:87], v[102:103], v[86:87], v[98:99]
	v_pk_mul_f32 v[106:107], v[106:107], s[26:27] op_sel_hi:[1,0]
	v_pk_mul_f32 v[86:87], v[86:87], s[26:27] op_sel_hi:[1,0]
	v_pk_fma_f32 v[60:61], v[60:61], 0.5, v[106:107] op_sel_hi:[1,0,1]
	v_pk_fma_f32 v[62:63], v[62:63], 0.5, v[86:87] op_sel_hi:[1,0,1]
	s_waitcnt vmcnt(4)
	v_lshlrev_b32_e32 v87, 16, v73
	v_and_b32_e32 v73, 0xffff0000, v73
	v_cvt_pk_bf16_f32 v240, v60, v61
	v_cvt_pk_bf16_f32 v241, v62, v63
	v_lshlrev_b32_e32 v86, 16, v72
	v_and_b32_e32 v72, 0xffff0000, v72
	v_sub_f32_e32 v63, v73, v74
	v_sub_f32_e32 v62, v87, v74
	v_sub_f32_e32 v61, v72, v74
	v_sub_f32_e32 v60, v86, v74
	v_pk_mul_f32 v[62:63], v[74:75], v[62:63] op_sel:[1,0]
	v_pk_mul_f32 v[60:61], v[74:75], v[60:61] op_sel:[1,0]
	v_pk_fma_f32 v[62:63], v[90:91], v[62:63], v[94:95]
	v_pk_fma_f32 v[60:61], v[88:89], v[60:61], v[92:93]
	v_cndmask_b32_e64 v63, v63, v73, s[8:9]
	v_cndmask_b32_e64 v62, v62, v87, s[8:9]
	v_cndmask_b32_e64 v61, v61, v72, s[8:9]
	v_cndmask_b32_e64 v60, v60, v86, s[8:9]
	v_pk_mul_f32 v[62:63], v[62:63], s[26:27] op_sel_hi:[1,0]
	v_pk_mul_f32 v[60:61], v[60:61], s[26:27] op_sel_hi:[1,0]
	v_pk_fma_f32 v[58:59], v[58:59], 0.5, v[62:63] op_sel_hi:[1,0,1]
	global_load_dwordx2 v[62:63], v[108:109], off offset:32
	v_pk_fma_f32 v[56:57], v[56:57], 0.5, v[60:61] op_sel_hi:[1,0,1]
	s_waitcnt vmcnt(4)
	v_lshlrev_b32_e32 v60, 16, v70
	v_and_b32_e32 v61, 0xffff0000, v70
	v_lshlrev_b32_e32 v70, 16, v71
	v_and_b32_e32 v71, 0xffff0000, v71
	v_cvt_pk_bf16_f32 v242, v56, v57
	v_cvt_pk_bf16_f32 v243, v58, v59
	v_sub_f32_e32 v59, v71, v74
	v_sub_f32_e32 v58, v70, v74
	v_pk_mul_f32 v[58:59], v[74:75], v[58:59] op_sel:[1,0]
	s_nop 1
	v_permlane16_swap_b32_e32 v240, v242
	v_permlane16_swap_b32_e32 v241, v243
	v_lshl_add_u64 v[248:249], v[104:105], 0, v[250:251]
	global_store_dwordx4 v[248:249], v[240:243], off
	v_pk_fma_f32 v[58:59], v[78:79], v[58:59], v[82:83]
	v_sub_f32_e32 v57, v61, v74
	v_cndmask_b32_e64 v59, v59, v71, s[8:9]
	v_cndmask_b32_e64 v58, v58, v70, s[8:9]
	v_pk_mul_f32 v[58:59], v[58:59], s[26:27] op_sel_hi:[1,0]
	v_sub_f32_e32 v56, v60, v74
	v_pk_fma_f32 v[54:55], v[54:55], 0.5, v[58:59] op_sel_hi:[1,0,1]
	global_load_dwordx2 v[58:59], v[108:109], off offset:256
	v_pk_mul_f32 v[56:57], v[74:75], v[56:57] op_sel:[1,0]
	s_nop 0
	v_pk_fma_f32 v[56:57], v[76:77], v[56:57], v[80:81]
	s_nop 0
	v_cndmask_b32_e64 v57, v57, v61, s[8:9]
	v_cndmask_b32_e64 v56, v56, v60, s[8:9]
	v_pk_mul_f32 v[56:57], v[56:57], s[26:27] op_sel_hi:[1,0]
	s_waitcnt vmcnt(5)
	v_lshlrev_b32_e32 v60, 16, v85
	v_pk_fma_f32 v[52:53], v[52:53], 0.5, v[56:57] op_sel_hi:[1,0,1]
	v_lshlrev_b32_e32 v56, 16, v84
	v_cvt_pk_bf16_f32 v244, v52, v53
	v_cvt_pk_bf16_f32 v245, v54, v55
	v_and_b32_e32 v57, 0xffff0000, v84
	v_and_b32_e32 v61, 0xffff0000, v85
	v_sub_f32_e32 v53, v57, v74
	v_sub_f32_e32 v52, v56, v74
	v_sub_f32_e32 v55, v61, v74
	v_sub_f32_e32 v54, v60, v74
	v_pk_mul_f32 v[54:55], v[74:75], v[54:55] op_sel:[1,0]
	v_pk_mul_f32 v[52:53], v[74:75], v[52:53] op_sel:[1,0]
	v_pk_fma_f32 v[54:55], v[134:135], v[54:55], v[138:139]
	v_pk_fma_f32 v[52:53], v[132:133], v[52:53], v[136:137]
	v_cndmask_b32_e64 v55, v55, v61, s[8:9]
	v_cndmask_b32_e64 v54, v54, v60, s[8:9]
	v_cndmask_b32_e64 v53, v53, v57, s[8:9]
	v_cndmask_b32_e64 v52, v52, v56, s[8:9]
	v_pk_mul_f32 v[52:53], v[52:53], s[26:27] op_sel_hi:[1,0]
	v_pk_mul_f32 v[54:55], v[54:55], s[26:27] op_sel_hi:[1,0]
	v_pk_fma_f32 v[44:45], v[44:45], 0.5, v[52:53] op_sel_hi:[1,0,1]
	v_pk_fma_f32 v[46:47], v[46:47], 0.5, v[54:55] op_sel_hi:[1,0,1]
	v_cvt_pk_bf16_f32 v246, v44, v45
	v_cvt_pk_bf16_f32 v247, v46, v47
	global_load_dwordx2 v[54:55], v[108:109], off offset:288
	s_waitcnt vmcnt(4)
; #define GASP __attribute__((address_space(1)))
;     __device__ __forceinline__ void operator()(Acc& acc, const Unit& u, int wr, int wc, int fr, int fq, LAS unsigned char* lds) const {
;     ...
;                 const float* rp = (row < split) ? res0 + (size_t)row * D : res1 + (size_t)(row - split) * D;
;                 float* op = out + (size_t)row * D;
;                 f32x2 st = (f32x2){0.f, 1.f}; if (STp) st = SL[rl];
;                 float s = 0.f, q = 0.f;
; #pragma unroll
;                 for (int bj = 0; bj < 2; ++bj)
; #pragma unroll
;                     for (int n = 0; n < 2; ++n) { const int c = col0 + bj * HALF + n * 16; f32x4 r;
;                         if (resb) { const u32x2 w = *(const GASP u32x2*)(resb + (size_t)row * D + c);
;                             r = (f32x4){__uint_as_float(w.x << 16), __uint_as_float(w.x & 0xffff0000u), __uint_as_float(w.y << 16), __uint_as_float(w.y & 0xffff0000u)}; }
;                         else r = *(const GASP f32x4*)(rp + c);
;                         if (STp) r = (r - st[0]) * st[1] * gg[bj][n] + bb[bj][n];
;                         const f32x4 o = r * ALPHA + acc[ai][bj][m][n] * scale;
;                         if (out) *(GASP f32x4*)(op + c) = o;
;                         if (ob) { u32x2 w; w.x = pk2(o[0], o[1]); w.y = pk2(o[2], o[3]); *(GASP u32x2*)(ob + (size_t)row * D + c) = w; }
	v_lshlrev_b32_e32 v46, 16, v110
	s_nop 1
	v_permlane16_swap_b32_e32 v244, v246
	v_permlane16_swap_b32_e32 v245, v247
	global_store_dwordx4 v[248:249], v[244:247], off offset:256
	v_lshlrev_b32_e32 v44, 16, v111
	v_and_b32_e32 v45, 0xffff0000, v111
	s_waitcnt lgkmcnt(2)
	v_sub_f32_e32 v45, v45, v66
	v_sub_f32_e32 v44, v44, v66
	v_pk_mul_f32 v[44:45], v[66:67], v[44:45] op_sel:[1,0]
	v_and_b32_e32 v47, 0xffff0000, v110
	v_pk_fma_f32 v[52:53], v[102:103], v[44:45], v[98:99]
	v_add_u32_e32 v44, s36, v207
	v_ashrrev_i32_e32 v45, 31, v44
	v_cmp_gt_i32_e32 vcc, s56, v44
	v_sub_f32_e32 v47, v47, v66
	v_sub_f32_e32 v46, v46, v66
	v_cndmask_b32_e32 v45, 0, v45, vcc
	v_lshlrev_b64 v[44:45], 11, v[44:45]
	v_lshl_add_u64 v[44:45], s[42:43], 0, v[44:45]
	v_lshl_add_u64 v[44:45], v[44:45], 0, v[172:173]
	global_load_dwordx2 v[56:57], v[44:45], off
	v_pk_mul_f32 v[46:47], v[66:67], v[46:47] op_sel:[1,0]
	v_pk_mul_f32 v[52:53], v[52:53], s[26:27] op_sel_hi:[1,0]
	v_pk_fma_f32 v[46:47], v[100:101], v[46:47], v[96:97]
	v_pk_fma_f32 v[50:51], v[50:51], 0.5, v[52:53] op_sel_hi:[1,0,1]
	v_pk_mul_f32 v[46:47], v[46:47], s[26:27] op_sel_hi:[1,0]
	s_waitcnt vmcnt(5)
	v_lshlrev_b32_e32 v52, 16, v63
	v_pk_fma_f32 v[46:47], v[48:49], 0.5, v[46:47] op_sel_hi:[1,0,1]
	v_and_b32_e32 v53, 0xffff0000, v63
	v_cvt_pk_bf16_f32 v240, v46, v47
	v_cvt_pk_bf16_f32 v241, v50, v51
	v_lshlrev_b32_e32 v50, 16, v62
	v_and_b32_e32 v51, 0xffff0000, v62
	v_sub_f32_e32 v49, v53, v66
	v_sub_f32_e32 v48, v52, v66
	v_sub_f32_e32 v47, v51, v66
	v_sub_f32_e32 v46, v50, v66
	v_pk_mul_f32 v[48:49], v[66:67], v[48:49] op_sel:[1,0]
	v_pk_mul_f32 v[46:47], v[66:67], v[46:47] op_sel:[1,0]
	v_pk_fma_f32 v[48:49], v[90:91], v[48:49], v[94:95]
	v_pk_fma_f32 v[46:47], v[88:89], v[46:47], v[92:93]
	v_cndmask_b32_e64 v49, v49, v53, s[8:9]
	v_cndmask_b32_e64 v48, v48, v52, s[8:9]
	v_cndmask_b32_e64 v47, v47, v51, s[8:9]
	v_cndmask_b32_e64 v46, v46, v50, s[8:9]
	v_pk_mul_f32 v[48:49], v[48:49], s[26:27] op_sel_hi:[1,0]
	v_pk_mul_f32 v[46:47], v[46:47], s[26:27] op_sel_hi:[1,0]
	v_pk_fma_f32 v[42:43], v[42:43], 0.5, v[48:49] op_sel_hi:[1,0,1]
	global_load_dwordx2 v[48:49], v[44:45], off offset:32
	v_pk_fma_f32 v[40:41], v[40:41], 0.5, v[46:47] op_sel_hi:[1,0,1]
	s_waitcnt vmcnt(4)
	v_lshlrev_b32_e32 v50, 16, v59
	v_and_b32_e32 v51, 0xffff0000, v59
	v_cvt_pk_bf16_f32 v242, v40, v41
	v_cvt_pk_bf16_f32 v243, v42, v43
	v_sub_f32_e32 v43, v51, v66
	v_sub_f32_e32 v42, v50, v66
	v_pk_mul_f32 v[42:43], v[66:67], v[42:43] op_sel:[1,0]
	v_lshlrev_b32_e32 v46, 16, v58
	v_pk_fma_f32 v[42:43], v[78:79], v[42:43], v[82:83]
	v_and_b32_e32 v47, 0xffff0000, v58
	v_cndmask_b32_e64 v43, v43, v51, s[8:9]
	v_cndmask_b32_e64 v42, v42, v50, s[8:9]
	v_pk_mul_f32 v[42:43], v[42:43], s[26:27] op_sel_hi:[1,0]
	s_nop 1
	v_permlane16_swap_b32_e32 v240, v242
	v_permlane16_swap_b32_e32 v241, v243
	v_lshl_add_u64 v[248:249], v[108:109], 0, v[250:251]
	global_store_dwordx4 v[248:249], v[240:243], off
	v_pk_fma_f32 v[38:39], v[38:39], 0.5, v[42:43] op_sel_hi:[1,0,1]
	global_load_dwordx2 v[42:43], v[44:45], off offset:256
	v_sub_f32_e32 v41, v47, v66
	v_sub_f32_e32 v40, v46, v66
	v_pk_mul_f32 v[40:41], v[66:67], v[40:41] op_sel:[1,0]
	s_nop 0
	v_pk_fma_f32 v[40:41], v[76:77], v[40:41], v[80:81]
	s_nop 0
	v_cndmask_b32_e64 v41, v41, v47, s[8:9]
	v_cndmask_b32_e64 v40, v40, v46, s[8:9]
	v_pk_mul_f32 v[40:41], v[40:41], s[26:27] op_sel_hi:[1,0]
	s_waitcnt vmcnt(5)
	v_lshlrev_b32_e32 v46, 16, v55
	v_pk_fma_f32 v[36:37], v[36:37], 0.5, v[40:41] op_sel_hi:[1,0,1]
	v_lshlrev_b32_e32 v40, 16, v54
	v_cvt_pk_bf16_f32 v244, v36, v37
	v_cvt_pk_bf16_f32 v245, v38, v39
	v_and_b32_e32 v41, 0xffff0000, v54
	v_and_b32_e32 v47, 0xffff0000, v55
	v_sub_f32_e32 v37, v41, v66
	v_sub_f32_e32 v36, v40, v66
	v_sub_f32_e32 v39, v47, v66
	v_sub_f32_e32 v38, v46, v66
	v_pk_mul_f32 v[38:39], v[66:67], v[38:39] op_sel:[1,0]
	v_pk_mul_f32 v[36:37], v[66:67], v[36:37] op_sel:[1,0]
	v_pk_fma_f32 v[38:39], v[134:135], v[38:39], v[138:139]
	v_pk_fma_f32 v[36:37], v[132:133], v[36:37], v[136:137]
	v_cndmask_b32_e64 v39, v39, v47, s[8:9]
	v_cndmask_b32_e64 v38, v38, v46, s[8:9]
	v_cndmask_b32_e64 v37, v37, v41, s[8:9]
	v_cndmask_b32_e64 v36, v36, v40, s[8:9]
	v_pk_mul_f32 v[36:37], v[36:37], s[26:27] op_sel_hi:[1,0]
	v_pk_mul_f32 v[38:39], v[38:39], s[26:27] op_sel_hi:[1,0]
	v_pk_fma_f32 v[28:29], v[28:29], 0.5, v[36:37] op_sel_hi:[1,0,1]
	v_pk_fma_f32 v[30:31], v[30:31], 0.5, v[38:39] op_sel_hi:[1,0,1]
	v_cvt_pk_bf16_f32 v246, v28, v29
	v_cvt_pk_bf16_f32 v247, v30, v31
	global_load_dwordx2 v[38:39], v[44:45], off offset:288
	s_waitcnt vmcnt(4)
	v_lshlrev_b32_e32 v30, 16, v56
	s_nop 1
	v_permlane16_swap_b32_e32 v244, v246
	v_permlane16_swap_b32_e32 v245, v247
	global_store_dwordx4 v[248:249], v[244:247], off offset:256
	v_lshlrev_b32_e32 v28, 16, v57
	v_and_b32_e32 v29, 0xffff0000, v57
	s_waitcnt lgkmcnt(1)
	v_sub_f32_e32 v29, v29, v64
	v_sub_f32_e32 v28, v28, v64
	v_pk_mul_f32 v[28:29], v[64:65], v[28:29] op_sel:[1,0]
	v_and_b32_e32 v31, 0xffff0000, v56
	v_pk_fma_f32 v[36:37], v[102:103], v[28:29], v[98:99]
	v_add_u32_e32 v28, s36, v211
	v_ashrrev_i32_e32 v29, 31, v28
	v_cmp_gt_i32_e32 vcc, s56, v28
	v_sub_f32_e32 v31, v31, v64
	v_sub_f32_e32 v30, v30, v64
	v_cndmask_b32_e32 v29, 0, v29, vcc
	v_lshlrev_b64 v[28:29], 11, v[28:29]
	v_lshl_add_u64 v[28:29], s[42:43], 0, v[28:29]
	v_lshl_add_u64 v[28:29], v[28:29], 0, v[172:173]
	global_load_dwordx2 v[40:41], v[28:29], off
	v_pk_mul_f32 v[30:31], v[64:65], v[30:31] op_sel:[1,0]
	v_pk_mul_f32 v[36:37], v[36:37], s[26:27] op_sel_hi:[1,0]
	v_pk_fma_f32 v[30:31], v[100:101], v[30:31], v[96:97]
	v_pk_fma_f32 v[34:35], v[34:35], 0.5, v[36:37] op_sel_hi:[1,0,1]
	v_pk_mul_f32 v[30:31], v[30:31], s[26:27] op_sel_hi:[1,0]
	s_waitcnt vmcnt(5)
; #define GASP __attribute__((address_space(1)))
;     __device__ __forceinline__ void operator()(Acc& acc, const Unit& u, int wr, int wc, int fr, int fq, LAS unsigned char* lds) const {
;     ...
;                 const float* rp = (row < split) ? res0 + (size_t)row * D : res1 + (size_t)(row - split) * D;
;                 float* op = out + (size_t)row * D;
;                 f32x2 st = (f32x2){0.f, 1.f}; if (STp) st = SL[rl];
;                 float s = 0.f, q = 0.f;
; #pragma unroll
;                 for (int bj = 0; bj < 2; ++bj)
; #pragma unroll
;                     for (int n = 0; n < 2; ++n) { const int c = col0 + bj * HALF + n * 16; f32x4 r;
;                         if (resb) { const u32x2 w = *(const GASP u32x2*)(resb + (size_t)row * D + c);
;                             r = (f32x4){__uint_as_float(w.x << 16), __uint_as_float(w.x & 0xffff0000u), __uint_as_float(w.y << 16), __uint_as_float(w.y & 0xffff0000u)}; }
;                         else r = *(const GASP f32x4*)(rp + c);
;                         if (STp) r = (r - st[0]) * st[1] * gg[bj][n] + bb[bj][n];
;                         const f32x4 o = r * ALPHA + acc[ai][bj][m][n] * scale;
;                         if (out) *(GASP f32x4*)(op + c) = o;
;                         if (ob) { u32x2 w; w.x = pk2(o[0], o[1]); w.y = pk2(o[2], o[3]); *(GASP u32x2*)(ob + (size_t)row * D + c) = w; }
	v_lshlrev_b32_e32 v36, 16, v48
	v_pk_fma_f32 v[30:31], v[32:33], 0.5, v[30:31] op_sel_hi:[1,0,1]
	v_and_b32_e32 v37, 0xffff0000, v48
	v_cvt_pk_bf16_f32 v240, v30, v31
	v_cvt_pk_bf16_f32 v241, v34, v35
	global_load_dwordx2 v[34:35], v[28:29], off offset:32
	v_lshlrev_b32_e32 v46, 16, v49
	v_and_b32_e32 v47, 0xffff0000, v49
	v_sub_f32_e32 v31, v37, v64
	v_sub_f32_e32 v30, v36, v64
	v_sub_f32_e32 v33, v47, v64
	v_sub_f32_e32 v32, v46, v64
	v_pk_mul_f32 v[32:33], v[64:65], v[32:33] op_sel:[1,0]
	v_pk_mul_f32 v[30:31], v[64:65], v[30:31] op_sel:[1,0]
	v_pk_fma_f32 v[32:33], v[90:91], v[32:33], v[94:95]
	v_pk_fma_f32 v[30:31], v[88:89], v[30:31], v[92:93]
	v_cndmask_b32_e64 v33, v33, v47, s[8:9]
	v_cndmask_b32_e64 v32, v32, v46, s[8:9]
	v_cndmask_b32_e64 v31, v31, v37, s[8:9]
	v_cndmask_b32_e64 v30, v30, v36, s[8:9]
	v_pk_mul_f32 v[30:31], v[30:31], s[26:27] op_sel_hi:[1,0]
	v_pk_mul_f32 v[32:33], v[32:33], s[26:27] op_sel_hi:[1,0]
	v_pk_fma_f32 v[24:25], v[24:25], 0.5, v[30:31] op_sel_hi:[1,0,1]
	v_pk_fma_f32 v[26:27], v[26:27], 0.5, v[32:33] op_sel_hi:[1,0,1]
	global_load_dwordx2 v[30:31], v[28:29], off offset:256
	v_cvt_pk_bf16_f32 v242, v24, v25
	v_cvt_pk_bf16_f32 v243, v26, v27
	s_waitcnt vmcnt(5)
	v_lshlrev_b32_e32 v32, 16, v42
	v_and_b32_e32 v33, 0xffff0000, v42
	s_nop 1
	v_permlane16_swap_b32_e32 v240, v242
	v_permlane16_swap_b32_e32 v241, v243
	v_lshl_add_u64 v[248:249], v[44:45], 0, v[250:251]
	global_store_dwordx4 v[248:249], v[240:243], off
	v_sub_f32_e32 v25, v33, v64
	v_sub_f32_e32 v24, v32, v64
	v_pk_mul_f32 v[24:25], v[64:65], v[24:25] op_sel:[1,0]
	v_lshlrev_b32_e32 v36, 16, v43
	v_pk_fma_f32 v[24:25], v[76:77], v[24:25], v[80:81]
	v_and_b32_e32 v37, 0xffff0000, v43
	v_cndmask_b32_e64 v25, v25, v33, s[8:9]
	v_cndmask_b32_e64 v24, v24, v32, s[8:9]
	v_pk_mul_f32 v[24:25], v[24:25], s[26:27] op_sel_hi:[1,0]
	v_sub_f32_e32 v27, v37, v64
	v_pk_fma_f32 v[20:21], v[20:21], 0.5, v[24:25] op_sel_hi:[1,0,1]
	global_load_dwordx2 v[24:25], v[28:29], off offset:288
	v_sub_f32_e32 v26, v36, v64
	v_pk_mul_f32 v[26:27], v[64:65], v[26:27] op_sel:[1,0]
	v_cvt_pk_bf16_f32 v244, v20, v21
	v_pk_fma_f32 v[26:27], v[78:79], v[26:27], v[82:83]
	s_and_b64 vcc, exec, s[10:11]
	v_cndmask_b32_e64 v27, v27, v37, s[8:9]
	v_cndmask_b32_e64 v26, v26, v36, s[8:9]
	v_pk_mul_f32 v[26:27], v[26:27], s[26:27] op_sel_hi:[1,0]
	s_mov_b64 s[10:11], -1
	v_pk_fma_f32 v[22:23], v[22:23], 0.5, v[26:27] op_sel_hi:[1,0,1]
	s_waitcnt vmcnt(6)
	v_lshlrev_b32_e32 v26, 16, v38
	v_cvt_pk_bf16_f32 v245, v22, v23
	v_and_b32_e32 v27, 0xffff0000, v38
	v_lshlrev_b32_e32 v32, 16, v39
	v_and_b32_e32 v33, 0xffff0000, v39
	v_sub_f32_e32 v21, v27, v64
	v_sub_f32_e32 v20, v26, v64
	v_sub_f32_e32 v23, v33, v64
	v_sub_f32_e32 v22, v32, v64
	v_pk_mul_f32 v[22:23], v[64:65], v[22:23] op_sel:[1,0]
	v_pk_mul_f32 v[20:21], v[64:65], v[20:21] op_sel:[1,0]
	v_pk_fma_f32 v[22:23], v[134:135], v[22:23], v[138:139]
	v_pk_fma_f32 v[20:21], v[132:133], v[20:21], v[136:137]
	v_cndmask_b32_e64 v23, v23, v33, s[8:9]
	v_cndmask_b32_e64 v22, v22, v32, s[8:9]
	v_cndmask_b32_e64 v21, v21, v27, s[8:9]
	v_cndmask_b32_e64 v20, v20, v26, s[8:9]
	v_pk_mul_f32 v[20:21], v[20:21], s[26:27] op_sel_hi:[1,0]
	v_pk_mul_f32 v[22:23], v[22:23], s[26:27] op_sel_hi:[1,0]
	v_pk_fma_f32 v[12:13], v[12:13], 0.5, v[20:21] op_sel_hi:[1,0,1]
	v_pk_fma_f32 v[14:15], v[14:15], 0.5, v[22:23] op_sel_hi:[1,0,1]
	v_cvt_pk_bf16_f32 v246, v12, v13
	v_cvt_pk_bf16_f32 v247, v14, v15
	s_nop 1
	v_permlane16_swap_b32_e32 v244, v246
	v_permlane16_swap_b32_e32 v245, v247
	global_store_dwordx4 v[248:249], v[244:247], off offset:256
	s_waitcnt vmcnt(5)
	v_lshlrev_b32_e32 v14, 16, v40
	v_and_b32_e32 v15, 0xffff0000, v40
	v_lshlrev_b32_e32 v12, 16, v41
	v_and_b32_e32 v13, 0xffff0000, v41
	s_waitcnt lgkmcnt(0)
; #define GASP __attribute__((address_space(1)))
;     __device__ __forceinline__ void operator()(Acc& acc, const Unit& u, int wr, int wc, int fr, int fq, LAS unsigned char* lds) const {
;     ...
;                 const float* rp = (row < split) ? res0 + (size_t)row * D : res1 + (size_t)(row - split) * D;
;                 float* op = out + (size_t)row * D;
;                 f32x2 st = (f32x2){0.f, 1.f}; if (STp) st = SL[rl];
;                 float s = 0.f, q = 0.f;
; #pragma unroll
;                 for (int bj = 0; bj < 2; ++bj)
; #pragma unroll
;                     for (int n = 0; n < 2; ++n) { const int c = col0 + bj * HALF + n * 16; f32x4 r;
;                         if (resb) { const u32x2 w = *(const GASP u32x2*)(resb + (size_t)row * D + c);
;                             r = (f32x4){__uint_as_float(w.x << 16), __uint_as_float(w.x & 0xffff0000u), __uint_as_float(w.y << 16), __uint_as_float(w.y & 0xffff0000u)}; }
;                         else r = *(const GASP f32x4*)(rp + c);
;                         if (STp) r = (r - st[0]) * st[1] * gg[bj][n] + bb[bj][n];
;                         const f32x4 o = r * ALPHA + acc[ai][bj][m][n] * scale;
;                         if (out) *(GASP f32x4*)(op + c) = o;
;                         if (ob) { u32x2 w; w.x = pk2(o[0], o[1]); w.y = pk2(o[2], o[3]); *(GASP u32x2*)(ob + (size_t)row * D + c) = w; }
	v_sub_f32_e32 v13, v13, v68
	v_sub_f32_e32 v12, v12, v68
	v_sub_f32_e32 v15, v15, v68
	v_sub_f32_e32 v14, v14, v68
	v_pk_mul_f32 v[14:15], v[68:69], v[14:15] op_sel:[1,0]
	v_pk_mul_f32 v[12:13], v[68:69], v[12:13] op_sel:[1,0]
	v_pk_fma_f32 v[14:15], v[100:101], v[14:15], v[96:97]
	v_pk_fma_f32 v[12:13], v[102:103], v[12:13], v[98:99]
	v_pk_mul_f32 v[14:15], v[14:15], s[26:27] op_sel_hi:[1,0]
	v_pk_mul_f32 v[12:13], v[12:13], s[26:27] op_sel_hi:[1,0]
	v_pk_fma_f32 v[14:15], v[16:17], 0.5, v[14:15] op_sel_hi:[1,0,1]
	v_pk_fma_f32 v[12:13], v[18:19], 0.5, v[12:13] op_sel_hi:[1,0,1]
	v_cvt_pk_bf16_f32 v240, v14, v15
	v_cvt_pk_bf16_f32 v241, v12, v13
	s_waitcnt vmcnt(4)
	v_lshlrev_b32_e32 v16, 16, v34
	v_and_b32_e32 v17, 0xffff0000, v34
	v_lshlrev_b32_e32 v18, 16, v35
	v_and_b32_e32 v19, 0xffff0000, v35
	v_sub_f32_e32 v13, v17, v68
	v_sub_f32_e32 v12, v16, v68
	v_sub_f32_e32 v15, v19, v68
	v_sub_f32_e32 v14, v18, v68
	v_pk_mul_f32 v[14:15], v[68:69], v[14:15] op_sel:[1,0]
	v_pk_mul_f32 v[12:13], v[68:69], v[12:13] op_sel:[1,0]
	v_pk_fma_f32 v[14:15], v[90:91], v[14:15], v[94:95]
	v_pk_fma_f32 v[12:13], v[88:89], v[12:13], v[92:93]
	v_cndmask_b32_e64 v15, v15, v19, s[8:9]
	v_cndmask_b32_e64 v14, v14, v18, s[8:9]
	v_cndmask_b32_e64 v13, v13, v17, s[8:9]
	v_cndmask_b32_e64 v12, v12, v16, s[8:9]
	v_pk_mul_f32 v[12:13], v[12:13], s[26:27] op_sel_hi:[1,0]
	v_pk_mul_f32 v[14:15], v[14:15], s[26:27] op_sel_hi:[1,0]
	v_pk_fma_f32 v[8:9], v[8:9], 0.5, v[12:13] op_sel_hi:[1,0,1]
	v_pk_fma_f32 v[10:11], v[10:11], 0.5, v[14:15] op_sel_hi:[1,0,1]
	v_cvt_pk_bf16_f32 v242, v8, v9
	v_cvt_pk_bf16_f32 v243, v10, v11
	s_waitcnt vmcnt(3)
	v_lshlrev_b32_e32 v12, 16, v30
	v_and_b32_e32 v13, 0xffff0000, v30
	v_lshlrev_b32_e32 v14, 16, v31
	v_and_b32_e32 v15, 0xffff0000, v31
	s_nop 1
	v_permlane16_swap_b32_e32 v240, v242
	v_permlane16_swap_b32_e32 v241, v243
	v_lshl_add_u64 v[248:249], v[28:29], 0, v[250:251]
	global_store_dwordx4 v[248:249], v[240:243], off
	v_sub_f32_e32 v9, v13, v68
	v_sub_f32_e32 v8, v12, v68
	v_sub_f32_e32 v11, v15, v68
	v_sub_f32_e32 v10, v14, v68
	v_pk_mul_f32 v[10:11], v[68:69], v[10:11] op_sel:[1,0]
	v_pk_mul_f32 v[8:9], v[68:69], v[8:9] op_sel:[1,0]
	v_pk_fma_f32 v[10:11], v[78:79], v[10:11], v[82:83]
	v_pk_fma_f32 v[8:9], v[76:77], v[8:9], v[80:81]
	v_cndmask_b32_e64 v11, v11, v15, s[8:9]
	v_cndmask_b32_e64 v10, v10, v14, s[8:9]
	v_cndmask_b32_e64 v9, v9, v13, s[8:9]
	v_cndmask_b32_e64 v8, v8, v12, s[8:9]
	v_pk_mul_f32 v[8:9], v[8:9], s[26:27] op_sel_hi:[1,0]
	v_pk_mul_f32 v[10:11], v[10:11], s[26:27] op_sel_hi:[1,0]
	v_pk_fma_f32 v[4:5], v[4:5], 0.5, v[8:9] op_sel_hi:[1,0,1]
	v_pk_fma_f32 v[6:7], v[6:7], 0.5, v[10:11] op_sel_hi:[1,0,1]
	v_cvt_pk_bf16_f32 v244, v4, v5
	v_cvt_pk_bf16_f32 v245, v6, v7
	s_waitcnt vmcnt(2)
	v_lshlrev_b32_e32 v8, 16, v24
	v_and_b32_e32 v9, 0xffff0000, v24
	v_lshlrev_b32_e32 v10, 16, v25
	v_and_b32_e32 v11, 0xffff0000, v25
	v_sub_f32_e32 v5, v9, v68
	v_sub_f32_e32 v4, v8, v68
	v_sub_f32_e32 v7, v11, v68
	v_sub_f32_e32 v6, v10, v68
	v_pk_mul_f32 v[6:7], v[68:69], v[6:7] op_sel:[1,0]
	v_pk_mul_f32 v[4:5], v[68:69], v[4:5] op_sel:[1,0]
	v_pk_fma_f32 v[6:7], v[134:135], v[6:7], v[138:139]
	v_pk_fma_f32 v[4:5], v[132:133], v[4:5], v[136:137]
	v_cndmask_b32_e64 v7, v7, v11, s[8:9]
	v_cndmask_b32_e64 v6, v6, v10, s[8:9]
	v_cndmask_b32_e64 v5, v5, v9, s[8:9]
	v_cndmask_b32_e64 v4, v4, v8, s[8:9]
	v_pk_mul_f32 v[4:5], v[4:5], s[26:27] op_sel_hi:[1,0]
	v_pk_mul_f32 v[6:7], v[6:7], s[26:27] op_sel_hi:[1,0]
	v_pk_fma_f32 v[0:1], v[0:1], 0.5, v[4:5] op_sel_hi:[1,0,1]
	v_pk_fma_f32 v[2:3], v[2:3], 0.5, v[6:7] op_sel_hi:[1,0,1]
	v_cvt_pk_bf16_f32 v246, v0, v1
	v_cvt_pk_bf16_f32 v247, v2, v3
	s_nop 1
	v_permlane16_swap_b32_e32 v244, v246
	v_permlane16_swap_b32_e32 v245, v247
	global_store_dwordx4 v[248:249], v[244:247], off offset:256
	s_cbranch_vccnz .LBB0_1633
	s_andn2_b64 vcc, exec, s[14:15]
	s_cbranch_vccnz .LBB0_1632
	s_barrier
	s_branch .LBB0_1632
